# rescaled RWKV scan, step order 2: prefetch LDS reads early in the step, v*kd products as the late DPP fillers
# baseline (speedup 1.0000x reference)
; template <int CTRL> __device__ __forceinline__ float dppf(float x) { return __builtin_bit_cast(float, __builtin_amdgcn_update_dpp(0, __builtin_bit_cast(int, x), CTRL, 0xF, 0xF, false)); }
; __device__ __forceinline__ void phase_rwkv_scan(const Fr& F, int jr) {
;     ...
;                 unsigned a1 = (unsigned)(size_t)(__attribute__((address_space(3))) float*)(Wv + ks), a2 = (unsigned)(size_t)(__attribute__((address_space(3))) float*)(Rr + ks),
;                          a3 = (unsigned)(size_t)(__attribute__((address_space(3))) float*)(Vv + rloc), a4 = (unsigned)(size_t)(__attribute__((address_space(3))) float*)(Ypw + lane);
;                 asm volatile("" : "+v"(a1), "+v"(a2), "+v"(a3), "+v"(a4));
;                 typedef const __attribute__((address_space(3))) f32x4* lp4; typedef const __attribute__((address_space(3))) float* lp1; typedef __attribute__((address_space(3))) float* lw1;
;                 const lp4 PW = (lp4)a1, PR = (lp4)a2; const lp1 PV = (lp1)a3; const lw1 PY = (lw1)a4;
;                 f32x4 w4 = PW[0], k4 = PW[1024], b4 = PW[2048], d4 = PW[3072], r4 = PR[0];
;                 float vv = PV[0];
;                 for (int pg = 0; pg < 64; pg += 16) {
; #pragma unroll
;                     for (int pi = 0; pi < 16; ++pi) {
;                         const int p = pg + pi, pn = p < 63 ? p + 1 : 63;
;                         const f32x4 w4n = PW[pn * 16], k4n = PW[1024 + pn * 16], b4n = PW[2048 + pn * 16], d4n = PW[3072 + pn * 16], r4n = PR[pn * 16];
;                         const float vvn = PV[pn * 32];
;                         f32x2 t = S01 * k4.xy; t = S23 * k4.zw + t; float sa = t.x + t.y;
;                         sa += dppf<0x128>(sa);
;                         const f32x2 dv01 = d4.xy * vv, dv23 = d4.zw * vv;
;                         sa += dppf<0x124>(sa);
;                         const f32x2 e01 = S01 * w4.xy + dv01;
;                         sa += dppf<0x122>(sa);
;                         const f32x2 e23 = S23 * w4.zw + dv23;
;                         sa += dppf<0x121>(sa);
;                         S01 = e01 - b4.xy * sa; S23 = e23 - b4.zw * sa;
;                         f32x2 u = S01 * r4.xy; u = S23 * r4.zw + u;
;                         PY[pi * 64] = u.x + u.y;
;                         w4 = w4n; k4 = k4n; b4 = b4n; d4 = d4n; r4 = r4n; vv = vvn;
.Lrw0_shc:
	v_add_u32_e32 v240, s11, v214
	v_add_u32_e32 v242, s11, v216
	ds_read_b128 v[84:87], v240 offset:8704
	ds_read_b128 v[56:59], v242 offset:43520
	ds_read_b128 v[92:95], v240 offset:26112
	ds_read_b128 v[88:91], v240 offset:17408
	ds_read_b128 v[96:99], v240 offset:34816
	ds_read_b128 v[106:109], v240 offset:8976
	ds_read_b128 v[114:117], v240 offset:26384
	ds_read_b128 v[110:113], v240 offset:17680
	s_waitcnt lgkmcnt(4)
	v_pk_mul_f32 v[226:227], v[206:207], v[84:85] op_sel_hi:[1,0]
	v_pk_fma_f32 v[232:233], v[56:57], v[92:93], v[206:207] op_sel_hi:[1,0,1]
	v_pk_fma_f32 v[226:227], v[208:209], v[84:85], v[226:227] op_sel:[0,1,0]
	v_pk_fma_f32 v[234:235], v[56:57], v[92:93], v[208:209] op_sel:[0,1,0]
	v_pk_fma_f32 v[226:227], v[210:211], v[86:87], v[226:227] op_sel_hi:[1,0,1]
	v_pk_fma_f32 v[236:237], v[56:57], v[94:95], v[210:211] op_sel_hi:[1,0,1]
	v_pk_fma_f32 v[226:227], v[212:213], v[86:87], v[226:227] op_sel:[0,1,0]
	v_pk_fma_f32 v[238:239], v[56:57], v[94:95], v[212:213] op_sel:[0,1,0]
	ds_read_b128 v[12:15], v240 offset:26656
	v_add_f32_dpp v230, v227, v226 row_ror:8 row_mask:0xf bank_mask:0xf
	ds_read_b128 v[8:11], v240 offset:17952
	ds_read_b128 v[4:7], v240 offset:9248
	v_add_f32_dpp v230, v230, v230 quad_perm:[1,0,3,2] row_mask:0xf bank_mask:0xf
	ds_read_b128 v[222:225], v240 offset:35088
	ds_read_b128 v[60:63], v242 offset:44048
	v_add_f32_dpp v230, v230, v230 quad_perm:[2,3,0,1] row_mask:0xf bank_mask:0xf
	s_nop 1
	v_add_f32_dpp v230, v230, v230 row_half_mirror row_mask:0xf bank_mask:0xf
	s_nop 1
	v_mov_b32_dpp v231, v230 row_ror:8 row_mask:0xf bank_mask:0xf
	v_pk_fma_f32 v[206:207], v[88:89], v[230:231], v[232:233] op_sel_hi:[0,1,1] neg_lo:[1,0,0] neg_hi:[1,0,0]
	v_pk_fma_f32 v[208:209], v[88:89], v[230:231], v[234:235] op_sel:[1,0,0] neg_lo:[1,0,0] neg_hi:[1,0,0]
	v_pk_fma_f32 v[210:211], v[90:91], v[230:231], v[236:237] op_sel_hi:[0,1,1] neg_lo:[1,0,0] neg_hi:[1,0,0]
	v_pk_fma_f32 v[212:213], v[90:91], v[230:231], v[238:239] op_sel:[1,0,0] neg_lo:[1,0,0] neg_hi:[1,0,0]
	s_waitcnt lgkmcnt(5)
	v_pk_mul_f32 v[226:227], v[206:207], v[106:107] op_sel_hi:[1,0]
	v_pk_mul_f32 v[228:229], v[206:207], v[96:97] op_sel_hi:[1,0]
	v_pk_fma_f32 v[226:227], v[208:209], v[106:107], v[226:227] op_sel:[0,1,0]
	v_pk_fma_f32 v[228:229], v[208:209], v[96:97], v[228:229] op_sel:[0,1,0]
	v_pk_fma_f32 v[226:227], v[210:211], v[108:109], v[226:227] op_sel_hi:[1,0,1]
	v_pk_fma_f32 v[228:229], v[210:211], v[98:99], v[228:229] op_sel_hi:[1,0,1]
	v_pk_fma_f32 v[226:227], v[212:213], v[108:109], v[226:227] op_sel:[0,1,0]
	v_pk_fma_f32 v[228:229], v[212:213], v[98:99], v[228:229] op_sel:[0,1,0]
	ds_read_b128 v[84:87], v240 offset:9520
	v_add_f32_dpp v230, v227, v226 row_ror:8 row_mask:0xf bank_mask:0xf
	ds_read_b128 v[92:95], v240 offset:26928
	ds_read_b128 v[88:91], v240 offset:18224
	v_add_f32_dpp v230, v230, v230 quad_perm:[1,0,3,2] row_mask:0xf bank_mask:0xf
	ds_read_b128 v[96:99], v240 offset:35360
	v_pk_fma_f32 v[232:233], v[58:59], v[114:115], v[206:207] op_sel_hi:[1,0,1]
	v_add_f32_dpp v230, v230, v230 quad_perm:[2,3,0,1] row_mask:0xf bank_mask:0xf
	v_pk_fma_f32 v[234:235], v[58:59], v[114:115], v[208:209] op_sel:[0,1,0]
	v_pk_fma_f32 v[236:237], v[58:59], v[116:117], v[210:211] op_sel_hi:[1,0,1]
	v_add_f32_dpp v230, v230, v230 row_half_mirror row_mask:0xf bank_mask:0xf
	ds_write_b64 v217, v[228:229] offset:0
	v_pk_fma_f32 v[238:239], v[58:59], v[116:117], v[212:213] op_sel:[0,1,0]
	v_mov_b32_dpp v231, v230 row_ror:8 row_mask:0xf bank_mask:0xf
	v_pk_fma_f32 v[206:207], v[110:111], v[230:231], v[232:233] op_sel_hi:[0,1,1] neg_lo:[1,0,0] neg_hi:[1,0,0]
	v_pk_fma_f32 v[208:209], v[110:111], v[230:231], v[234:235] op_sel:[1,0,0] neg_lo:[1,0,0] neg_hi:[1,0,0]
	v_pk_fma_f32 v[210:211], v[112:113], v[230:231], v[236:237] op_sel_hi:[0,1,1] neg_lo:[1,0,0] neg_hi:[1,0,0]
	v_pk_fma_f32 v[212:213], v[112:113], v[230:231], v[238:239] op_sel:[1,0,0] neg_lo:[1,0,0] neg_hi:[1,0,0]
	s_waitcnt lgkmcnt(5)
	ds_read_b128 v[56:59], v242 offset:44576
	v_pk_mul_f32 v[226:227], v[206:207], v[4:5] op_sel_hi:[1,0]
	v_pk_mul_f32 v[228:229], v[206:207], v[222:223] op_sel_hi:[1,0]
	v_pk_fma_f32 v[226:227], v[208:209], v[4:5], v[226:227] op_sel:[0,1,0]
	v_pk_fma_f32 v[228:229], v[208:209], v[222:223], v[228:229] op_sel:[0,1,0]
	v_pk_fma_f32 v[226:227], v[210:211], v[6:7], v[226:227] op_sel_hi:[1,0,1]
	v_pk_fma_f32 v[228:229], v[210:211], v[224:225], v[228:229] op_sel_hi:[1,0,1]
	v_pk_fma_f32 v[226:227], v[212:213], v[6:7], v[226:227] op_sel:[0,1,0]
	v_pk_fma_f32 v[228:229], v[212:213], v[224:225], v[228:229] op_sel:[0,1,0]
	ds_read_b128 v[106:109], v240 offset:9792
	v_add_f32_dpp v230, v227, v226 row_ror:8 row_mask:0xf bank_mask:0xf
	ds_read_b128 v[114:117], v240 offset:27200
	ds_read_b128 v[110:113], v240 offset:18496
	v_add_f32_dpp v230, v230, v230 quad_perm:[1,0,3,2] row_mask:0xf bank_mask:0xf
	ds_read_b128 v[222:225], v240 offset:35632
	v_pk_fma_f32 v[232:233], v[60:61], v[12:13], v[206:207] op_sel_hi:[1,0,1]
	v_add_f32_dpp v230, v230, v230 quad_perm:[2,3,0,1] row_mask:0xf bank_mask:0xf
	v_pk_fma_f32 v[234:235], v[60:61], v[12:13], v[208:209] op_sel:[0,1,0]
	v_pk_fma_f32 v[236:237], v[60:61], v[14:15], v[210:211] op_sel_hi:[1,0,1]
	v_add_f32_dpp v230, v230, v230 row_half_mirror row_mask:0xf bank_mask:0xf
	ds_write_b64 v217, v[228:229] offset:576
	v_pk_fma_f32 v[238:239], v[60:61], v[14:15], v[212:213] op_sel:[0,1,0]
	v_mov_b32_dpp v231, v230 row_ror:8 row_mask:0xf bank_mask:0xf
	v_pk_fma_f32 v[206:207], v[8:9], v[230:231], v[232:233] op_sel_hi:[0,1,1] neg_lo:[1,0,0] neg_hi:[1,0,0]
	v_pk_fma_f32 v[208:209], v[8:9], v[230:231], v[234:235] op_sel:[1,0,0] neg_lo:[1,0,0] neg_hi:[1,0,0]
	v_pk_fma_f32 v[210:211], v[10:11], v[230:231], v[236:237] op_sel_hi:[0,1,1] neg_lo:[1,0,0] neg_hi:[1,0,0]
	v_pk_fma_f32 v[212:213], v[10:11], v[230:231], v[238:239] op_sel:[1,0,0] neg_lo:[1,0,0] neg_hi:[1,0,0]
	s_waitcnt lgkmcnt(7)
; template <int CTRL> __device__ __forceinline__ float dppf(float x) { return __builtin_bit_cast(float, __builtin_amdgcn_update_dpp(0, __builtin_bit_cast(int, x), CTRL, 0xF, 0xF, false)); }
; __device__ __forceinline__ void phase_rwkv_scan(const Fr& F, int jr) {
;     ...
;                         const f32x4 w4n = PW[pn * 16], k4n = PW[1024 + pn * 16], b4n = PW[2048 + pn * 16], d4n = PW[3072 + pn * 16], r4n = PR[pn * 16];
;                         const float vvn = PV[pn * 32];
;                         f32x2 t = S01 * k4.xy; t = S23 * k4.zw + t; float sa = t.x + t.y;
;                         sa += dppf<0x128>(sa);
;                         const f32x2 dv01 = d4.xy * vv, dv23 = d4.zw * vv;
;                         sa += dppf<0x124>(sa);
;                         const f32x2 e01 = S01 * w4.xy + dv01;
;                         sa += dppf<0x122>(sa);
;                         const f32x2 e23 = S23 * w4.zw + dv23;
;                         sa += dppf<0x121>(sa);
;                         S01 = e01 - b4.xy * sa; S23 = e23 - b4.zw * sa;
;                         f32x2 u = S01 * r4.xy; u = S23 * r4.zw + u;
;                         PY[pi * 64] = u.x + u.y;
;                         w4 = w4n; k4 = k4n; b4 = b4n; d4 = d4n; r4 = r4n; vv = vvn;
	v_pk_mul_f32 v[226:227], v[206:207], v[84:85] op_sel_hi:[1,0]
	v_pk_mul_f32 v[228:229], v[206:207], v[96:97] op_sel_hi:[1,0]
	v_pk_fma_f32 v[226:227], v[208:209], v[84:85], v[226:227] op_sel:[0,1,0]
	v_pk_fma_f32 v[228:229], v[208:209], v[96:97], v[228:229] op_sel:[0,1,0]
	v_pk_fma_f32 v[226:227], v[210:211], v[86:87], v[226:227] op_sel_hi:[1,0,1]
	v_pk_fma_f32 v[228:229], v[210:211], v[98:99], v[228:229] op_sel_hi:[1,0,1]
	v_pk_fma_f32 v[226:227], v[212:213], v[86:87], v[226:227] op_sel:[0,1,0]
	v_pk_fma_f32 v[228:229], v[212:213], v[98:99], v[228:229] op_sel:[0,1,0]
	ds_read_b128 v[4:7], v240 offset:10064
	v_add_f32_dpp v230, v227, v226 row_ror:8 row_mask:0xf bank_mask:0xf
	ds_read_b128 v[12:15], v240 offset:27472
	ds_read_b128 v[8:11], v240 offset:18768
	v_add_f32_dpp v230, v230, v230 quad_perm:[1,0,3,2] row_mask:0xf bank_mask:0xf
	ds_read_b128 v[96:99], v240 offset:35904
	v_pk_fma_f32 v[232:233], v[62:63], v[92:93], v[206:207] op_sel_hi:[1,0,1]
	v_add_f32_dpp v230, v230, v230 quad_perm:[2,3,0,1] row_mask:0xf bank_mask:0xf
	v_pk_fma_f32 v[234:235], v[62:63], v[92:93], v[208:209] op_sel:[0,1,0]
	v_pk_fma_f32 v[236:237], v[62:63], v[94:95], v[210:211] op_sel_hi:[1,0,1]
	v_add_f32_dpp v230, v230, v230 row_half_mirror row_mask:0xf bank_mask:0xf
	ds_write_b64 v217, v[228:229] offset:1152
	v_pk_fma_f32 v[238:239], v[62:63], v[94:95], v[212:213] op_sel:[0,1,0]
	v_mov_b32_dpp v231, v230 row_ror:8 row_mask:0xf bank_mask:0xf
	v_pk_fma_f32 v[206:207], v[88:89], v[230:231], v[232:233] op_sel_hi:[0,1,1] neg_lo:[1,0,0] neg_hi:[1,0,0]
	v_pk_fma_f32 v[208:209], v[88:89], v[230:231], v[234:235] op_sel:[1,0,0] neg_lo:[1,0,0] neg_hi:[1,0,0]
	v_pk_fma_f32 v[210:211], v[90:91], v[230:231], v[236:237] op_sel_hi:[0,1,1] neg_lo:[1,0,0] neg_hi:[1,0,0]
	v_pk_fma_f32 v[212:213], v[90:91], v[230:231], v[238:239] op_sel:[1,0,0] neg_lo:[1,0,0] neg_hi:[1,0,0]
	s_waitcnt lgkmcnt(6)
	ds_read_b128 v[60:63], v242 offset:45104
	v_pk_mul_f32 v[226:227], v[206:207], v[106:107] op_sel_hi:[1,0]
	v_pk_mul_f32 v[228:229], v[206:207], v[222:223] op_sel_hi:[1,0]
	v_pk_fma_f32 v[226:227], v[208:209], v[106:107], v[226:227] op_sel:[0,1,0]
	v_pk_fma_f32 v[228:229], v[208:209], v[222:223], v[228:229] op_sel:[0,1,0]
	v_pk_fma_f32 v[226:227], v[210:211], v[108:109], v[226:227] op_sel_hi:[1,0,1]
	v_pk_fma_f32 v[228:229], v[210:211], v[224:225], v[228:229] op_sel_hi:[1,0,1]
	v_pk_fma_f32 v[226:227], v[212:213], v[108:109], v[226:227] op_sel:[0,1,0]
	v_pk_fma_f32 v[228:229], v[212:213], v[224:225], v[228:229] op_sel:[0,1,0]
	ds_read_b128 v[84:87], v240 offset:10336
	v_add_f32_dpp v230, v227, v226 row_ror:8 row_mask:0xf bank_mask:0xf
	ds_read_b128 v[92:95], v240 offset:27744
	ds_read_b128 v[88:91], v240 offset:19040
	v_add_f32_dpp v230, v230, v230 quad_perm:[1,0,3,2] row_mask:0xf bank_mask:0xf
	ds_read_b128 v[222:225], v240 offset:36176
	v_pk_fma_f32 v[232:233], v[56:57], v[114:115], v[206:207] op_sel_hi:[1,0,1]
	v_add_f32_dpp v230, v230, v230 quad_perm:[2,3,0,1] row_mask:0xf bank_mask:0xf
	v_pk_fma_f32 v[234:235], v[56:57], v[114:115], v[208:209] op_sel:[0,1,0]
	v_pk_fma_f32 v[236:237], v[56:57], v[116:117], v[210:211] op_sel_hi:[1,0,1]
	v_add_f32_dpp v230, v230, v230 row_half_mirror row_mask:0xf bank_mask:0xf
	ds_write_b64 v217, v[228:229] offset:1728
	v_pk_fma_f32 v[238:239], v[56:57], v[116:117], v[212:213] op_sel:[0,1,0]
	v_mov_b32_dpp v231, v230 row_ror:8 row_mask:0xf bank_mask:0xf
	v_pk_fma_f32 v[206:207], v[110:111], v[230:231], v[232:233] op_sel_hi:[0,1,1] neg_lo:[1,0,0] neg_hi:[1,0,0]
	v_pk_fma_f32 v[208:209], v[110:111], v[230:231], v[234:235] op_sel:[1,0,0] neg_lo:[1,0,0] neg_hi:[1,0,0]
	v_pk_fma_f32 v[210:211], v[112:113], v[230:231], v[236:237] op_sel_hi:[0,1,1] neg_lo:[1,0,0] neg_hi:[1,0,0]
	v_pk_fma_f32 v[212:213], v[112:113], v[230:231], v[238:239] op_sel:[1,0,0] neg_lo:[1,0,0] neg_hi:[1,0,0]
	s_waitcnt lgkmcnt(7)
	v_pk_mul_f32 v[226:227], v[206:207], v[4:5] op_sel_hi:[1,0]
	v_pk_mul_f32 v[228:229], v[206:207], v[96:97] op_sel_hi:[1,0]
	v_pk_fma_f32 v[226:227], v[208:209], v[4:5], v[226:227] op_sel:[0,1,0]
	v_pk_fma_f32 v[228:229], v[208:209], v[96:97], v[228:229] op_sel:[0,1,0]
	v_pk_fma_f32 v[226:227], v[210:211], v[6:7], v[226:227] op_sel_hi:[1,0,1]
	v_pk_fma_f32 v[228:229], v[210:211], v[98:99], v[228:229] op_sel_hi:[1,0,1]
	v_pk_fma_f32 v[226:227], v[212:213], v[6:7], v[226:227] op_sel:[0,1,0]
	v_pk_fma_f32 v[228:229], v[212:213], v[98:99], v[228:229] op_sel:[0,1,0]
	ds_read_b128 v[106:109], v240 offset:10608
	v_add_f32_dpp v230, v227, v226 row_ror:8 row_mask:0xf bank_mask:0xf
	ds_read_b128 v[114:117], v240 offset:28016
	ds_read_b128 v[110:113], v240 offset:19312
	v_add_f32_dpp v230, v230, v230 quad_perm:[1,0,3,2] row_mask:0xf bank_mask:0xf
	ds_read_b128 v[96:99], v240 offset:36448
	v_pk_fma_f32 v[232:233], v[58:59], v[12:13], v[206:207] op_sel_hi:[1,0,1]
	v_add_f32_dpp v230, v230, v230 quad_perm:[2,3,0,1] row_mask:0xf bank_mask:0xf
	v_pk_fma_f32 v[234:235], v[58:59], v[12:13], v[208:209] op_sel:[0,1,0]
	v_pk_fma_f32 v[236:237], v[58:59], v[14:15], v[210:211] op_sel_hi:[1,0,1]
	v_add_f32_dpp v230, v230, v230 row_half_mirror row_mask:0xf bank_mask:0xf
	ds_write_b64 v217, v[228:229] offset:2304
	v_pk_fma_f32 v[238:239], v[58:59], v[14:15], v[212:213] op_sel:[0,1,0]
	v_mov_b32_dpp v231, v230 row_ror:8 row_mask:0xf bank_mask:0xf
	v_pk_fma_f32 v[206:207], v[8:9], v[230:231], v[232:233] op_sel_hi:[0,1,1] neg_lo:[1,0,0] neg_hi:[1,0,0]
	v_pk_fma_f32 v[208:209], v[8:9], v[230:231], v[234:235] op_sel:[1,0,0] neg_lo:[1,0,0] neg_hi:[1,0,0]
	v_pk_fma_f32 v[210:211], v[10:11], v[230:231], v[236:237] op_sel_hi:[0,1,1] neg_lo:[1,0,0] neg_hi:[1,0,0]
	v_pk_fma_f32 v[212:213], v[10:11], v[230:231], v[238:239] op_sel:[1,0,0] neg_lo:[1,0,0] neg_hi:[1,0,0]
	s_waitcnt lgkmcnt(6)
; template <int CTRL> __device__ __forceinline__ float dppf(float x) { return __builtin_bit_cast(float, __builtin_amdgcn_update_dpp(0, __builtin_bit_cast(int, x), CTRL, 0xF, 0xF, false)); }
; __device__ __forceinline__ void phase_rwkv_scan(const Fr& F, int jr) {
;     ...
;                         const f32x4 w4n = PW[pn * 16], k4n = PW[1024 + pn * 16], b4n = PW[2048 + pn * 16], d4n = PW[3072 + pn * 16], r4n = PR[pn * 16];
;                         const float vvn = PV[pn * 32];
;                         f32x2 t = S01 * k4.xy; t = S23 * k4.zw + t; float sa = t.x + t.y;
;                         sa += dppf<0x128>(sa);
;                         const f32x2 dv01 = d4.xy * vv, dv23 = d4.zw * vv;
;                         sa += dppf<0x124>(sa);
;                         const f32x2 e01 = S01 * w4.xy + dv01;
;                         sa += dppf<0x122>(sa);
;                         const f32x2 e23 = S23 * w4.zw + dv23;
;                         sa += dppf<0x121>(sa);
;                         S01 = e01 - b4.xy * sa; S23 = e23 - b4.zw * sa;
;                         f32x2 u = S01 * r4.xy; u = S23 * r4.zw + u;
;                         PY[pi * 64] = u.x + u.y;
;                         w4 = w4n; k4 = k4n; b4 = b4n; d4 = d4n; r4 = r4n; vv = vvn;
	ds_read_b128 v[56:59], v242 offset:45632
	v_pk_mul_f32 v[226:227], v[206:207], v[84:85] op_sel_hi:[1,0]
	v_pk_mul_f32 v[228:229], v[206:207], v[222:223] op_sel_hi:[1,0]
	v_pk_fma_f32 v[226:227], v[208:209], v[84:85], v[226:227] op_sel:[0,1,0]
	v_pk_fma_f32 v[228:229], v[208:209], v[222:223], v[228:229] op_sel:[0,1,0]
	v_pk_fma_f32 v[226:227], v[210:211], v[86:87], v[226:227] op_sel_hi:[1,0,1]
	v_pk_fma_f32 v[228:229], v[210:211], v[224:225], v[228:229] op_sel_hi:[1,0,1]
	v_pk_fma_f32 v[226:227], v[212:213], v[86:87], v[226:227] op_sel:[0,1,0]
	v_pk_fma_f32 v[228:229], v[212:213], v[224:225], v[228:229] op_sel:[0,1,0]
	ds_read_b128 v[4:7], v240 offset:10880
	v_add_f32_dpp v230, v227, v226 row_ror:8 row_mask:0xf bank_mask:0xf
	ds_read_b128 v[12:15], v240 offset:28288
	ds_read_b128 v[8:11], v240 offset:19584
	v_add_f32_dpp v230, v230, v230 quad_perm:[1,0,3,2] row_mask:0xf bank_mask:0xf
	ds_read_b128 v[222:225], v240 offset:36720
	v_pk_fma_f32 v[232:233], v[60:61], v[92:93], v[206:207] op_sel_hi:[1,0,1]
	v_add_f32_dpp v230, v230, v230 quad_perm:[2,3,0,1] row_mask:0xf bank_mask:0xf
	v_pk_fma_f32 v[234:235], v[60:61], v[92:93], v[208:209] op_sel:[0,1,0]
	v_pk_fma_f32 v[236:237], v[60:61], v[94:95], v[210:211] op_sel_hi:[1,0,1]
	v_add_f32_dpp v230, v230, v230 row_half_mirror row_mask:0xf bank_mask:0xf
	ds_write_b64 v217, v[228:229] offset:2880
	v_pk_fma_f32 v[238:239], v[60:61], v[94:95], v[212:213] op_sel:[0,1,0]
	v_mov_b32_dpp v231, v230 row_ror:8 row_mask:0xf bank_mask:0xf
	v_pk_fma_f32 v[206:207], v[88:89], v[230:231], v[232:233] op_sel_hi:[0,1,1] neg_lo:[1,0,0] neg_hi:[1,0,0]
	v_pk_fma_f32 v[208:209], v[88:89], v[230:231], v[234:235] op_sel:[1,0,0] neg_lo:[1,0,0] neg_hi:[1,0,0]
	v_pk_fma_f32 v[210:211], v[90:91], v[230:231], v[236:237] op_sel_hi:[0,1,1] neg_lo:[1,0,0] neg_hi:[1,0,0]
	v_pk_fma_f32 v[212:213], v[90:91], v[230:231], v[238:239] op_sel:[1,0,0] neg_lo:[1,0,0] neg_hi:[1,0,0]
	s_waitcnt lgkmcnt(7)
	v_pk_mul_f32 v[226:227], v[206:207], v[106:107] op_sel_hi:[1,0]
	v_pk_mul_f32 v[228:229], v[206:207], v[96:97] op_sel_hi:[1,0]
	v_pk_fma_f32 v[226:227], v[208:209], v[106:107], v[226:227] op_sel:[0,1,0]
	v_pk_fma_f32 v[228:229], v[208:209], v[96:97], v[228:229] op_sel:[0,1,0]
	v_pk_fma_f32 v[226:227], v[210:211], v[108:109], v[226:227] op_sel_hi:[1,0,1]
	v_pk_fma_f32 v[228:229], v[210:211], v[98:99], v[228:229] op_sel_hi:[1,0,1]
	v_pk_fma_f32 v[226:227], v[212:213], v[108:109], v[226:227] op_sel:[0,1,0]
	v_pk_fma_f32 v[228:229], v[212:213], v[98:99], v[228:229] op_sel:[0,1,0]
	ds_read_b128 v[84:87], v240 offset:11152
	v_add_f32_dpp v230, v227, v226 row_ror:8 row_mask:0xf bank_mask:0xf
	ds_read_b128 v[92:95], v240 offset:28560
	ds_read_b128 v[88:91], v240 offset:19856
	v_add_f32_dpp v230, v230, v230 quad_perm:[1,0,3,2] row_mask:0xf bank_mask:0xf
	ds_read_b128 v[96:99], v240 offset:36992
	v_pk_fma_f32 v[232:233], v[62:63], v[114:115], v[206:207] op_sel_hi:[1,0,1]
	v_add_f32_dpp v230, v230, v230 quad_perm:[2,3,0,1] row_mask:0xf bank_mask:0xf
	v_pk_fma_f32 v[234:235], v[62:63], v[114:115], v[208:209] op_sel:[0,1,0]
	v_pk_fma_f32 v[236:237], v[62:63], v[116:117], v[210:211] op_sel_hi:[1,0,1]
	v_add_f32_dpp v230, v230, v230 row_half_mirror row_mask:0xf bank_mask:0xf
	ds_write_b64 v217, v[228:229] offset:3456
	v_pk_fma_f32 v[238:239], v[62:63], v[116:117], v[212:213] op_sel:[0,1,0]
	v_mov_b32_dpp v231, v230 row_ror:8 row_mask:0xf bank_mask:0xf
	v_pk_fma_f32 v[206:207], v[110:111], v[230:231], v[232:233] op_sel_hi:[0,1,1] neg_lo:[1,0,0] neg_hi:[1,0,0]
	v_pk_fma_f32 v[208:209], v[110:111], v[230:231], v[234:235] op_sel:[1,0,0] neg_lo:[1,0,0] neg_hi:[1,0,0]
	v_pk_fma_f32 v[210:211], v[112:113], v[230:231], v[236:237] op_sel_hi:[0,1,1] neg_lo:[1,0,0] neg_hi:[1,0,0]
	v_pk_fma_f32 v[212:213], v[112:113], v[230:231], v[238:239] op_sel:[1,0,0] neg_lo:[1,0,0] neg_hi:[1,0,0]
	s_waitcnt lgkmcnt(6)
	ds_read_b128 v[60:63], v242 offset:46160
	v_pk_mul_f32 v[226:227], v[206:207], v[4:5] op_sel_hi:[1,0]
	v_pk_mul_f32 v[228:229], v[206:207], v[222:223] op_sel_hi:[1,0]
	v_pk_fma_f32 v[226:227], v[208:209], v[4:5], v[226:227] op_sel:[0,1,0]
	v_pk_fma_f32 v[228:229], v[208:209], v[222:223], v[228:229] op_sel:[0,1,0]
	v_pk_fma_f32 v[226:227], v[210:211], v[6:7], v[226:227] op_sel_hi:[1,0,1]
	v_pk_fma_f32 v[228:229], v[210:211], v[224:225], v[228:229] op_sel_hi:[1,0,1]
	v_pk_fma_f32 v[226:227], v[212:213], v[6:7], v[226:227] op_sel:[0,1,0]
	v_pk_fma_f32 v[228:229], v[212:213], v[224:225], v[228:229] op_sel:[0,1,0]
	ds_read_b128 v[106:109], v240 offset:11424
	v_add_f32_dpp v230, v227, v226 row_ror:8 row_mask:0xf bank_mask:0xf
	ds_read_b128 v[114:117], v240 offset:28832
	ds_read_b128 v[110:113], v240 offset:20128
	v_add_f32_dpp v230, v230, v230 quad_perm:[1,0,3,2] row_mask:0xf bank_mask:0xf
	ds_read_b128 v[222:225], v240 offset:37264
	v_pk_fma_f32 v[232:233], v[56:57], v[12:13], v[206:207] op_sel_hi:[1,0,1]
	v_add_f32_dpp v230, v230, v230 quad_perm:[2,3,0,1] row_mask:0xf bank_mask:0xf
	v_pk_fma_f32 v[234:235], v[56:57], v[12:13], v[208:209] op_sel:[0,1,0]
	v_pk_fma_f32 v[236:237], v[56:57], v[14:15], v[210:211] op_sel_hi:[1,0,1]
	v_add_f32_dpp v230, v230, v230 row_half_mirror row_mask:0xf bank_mask:0xf
	ds_write_b64 v217, v[228:229] offset:4032
	v_pk_fma_f32 v[238:239], v[56:57], v[14:15], v[212:213] op_sel:[0,1,0]
	v_mov_b32_dpp v231, v230 row_ror:8 row_mask:0xf bank_mask:0xf
	v_pk_fma_f32 v[206:207], v[8:9], v[230:231], v[232:233] op_sel_hi:[0,1,1] neg_lo:[1,0,0] neg_hi:[1,0,0]
	v_pk_fma_f32 v[208:209], v[8:9], v[230:231], v[234:235] op_sel:[1,0,0] neg_lo:[1,0,0] neg_hi:[1,0,0]
	v_pk_fma_f32 v[210:211], v[10:11], v[230:231], v[236:237] op_sel_hi:[0,1,1] neg_lo:[1,0,0] neg_hi:[1,0,0]
	v_pk_fma_f32 v[212:213], v[10:11], v[230:231], v[238:239] op_sel:[1,0,0] neg_lo:[1,0,0] neg_hi:[1,0,0]
	s_waitcnt lgkmcnt(7)
; template <int CTRL> __device__ __forceinline__ float dppf(float x) { return __builtin_bit_cast(float, __builtin_amdgcn_update_dpp(0, __builtin_bit_cast(int, x), CTRL, 0xF, 0xF, false)); }
; __device__ __forceinline__ void phase_rwkv_scan(const Fr& F, int jr) {
;     ...
;                         const f32x4 w4n = PW[pn * 16], k4n = PW[1024 + pn * 16], b4n = PW[2048 + pn * 16], d4n = PW[3072 + pn * 16], r4n = PR[pn * 16];
;                         const float vvn = PV[pn * 32];
;                         f32x2 t = S01 * k4.xy; t = S23 * k4.zw + t; float sa = t.x + t.y;
;                         sa += dppf<0x128>(sa);
;                         const f32x2 dv01 = d4.xy * vv, dv23 = d4.zw * vv;
;                         sa += dppf<0x124>(sa);
;                         const f32x2 e01 = S01 * w4.xy + dv01;
;                         sa += dppf<0x122>(sa);
;                         const f32x2 e23 = S23 * w4.zw + dv23;
;                         sa += dppf<0x121>(sa);
;                         S01 = e01 - b4.xy * sa; S23 = e23 - b4.zw * sa;
;                         f32x2 u = S01 * r4.xy; u = S23 * r4.zw + u;
;                         PY[pi * 64] = u.x + u.y;
;                         w4 = w4n; k4 = k4n; b4 = b4n; d4 = d4n; r4 = r4n; vv = vvn;
	v_pk_mul_f32 v[226:227], v[206:207], v[84:85] op_sel_hi:[1,0]
	v_pk_mul_f32 v[228:229], v[206:207], v[96:97] op_sel_hi:[1,0]
	v_pk_fma_f32 v[226:227], v[208:209], v[84:85], v[226:227] op_sel:[0,1,0]
	v_pk_fma_f32 v[228:229], v[208:209], v[96:97], v[228:229] op_sel:[0,1,0]
	v_pk_fma_f32 v[226:227], v[210:211], v[86:87], v[226:227] op_sel_hi:[1,0,1]
	v_pk_fma_f32 v[228:229], v[210:211], v[98:99], v[228:229] op_sel_hi:[1,0,1]
	v_pk_fma_f32 v[226:227], v[212:213], v[86:87], v[226:227] op_sel:[0,1,0]
	v_pk_fma_f32 v[228:229], v[212:213], v[98:99], v[228:229] op_sel:[0,1,0]
	ds_read_b128 v[4:7], v240 offset:11696
	v_add_f32_dpp v230, v227, v226 row_ror:8 row_mask:0xf bank_mask:0xf
	ds_read_b128 v[12:15], v240 offset:29104
	ds_read_b128 v[8:11], v240 offset:20400
	v_add_f32_dpp v230, v230, v230 quad_perm:[1,0,3,2] row_mask:0xf bank_mask:0xf
	ds_read_b128 v[96:99], v240 offset:37536
	v_pk_fma_f32 v[232:233], v[58:59], v[92:93], v[206:207] op_sel_hi:[1,0,1]
	v_add_f32_dpp v230, v230, v230 quad_perm:[2,3,0,1] row_mask:0xf bank_mask:0xf
	v_pk_fma_f32 v[234:235], v[58:59], v[92:93], v[208:209] op_sel:[0,1,0]
	v_pk_fma_f32 v[236:237], v[58:59], v[94:95], v[210:211] op_sel_hi:[1,0,1]
	v_add_f32_dpp v230, v230, v230 row_half_mirror row_mask:0xf bank_mask:0xf
	ds_write_b64 v217, v[228:229] offset:4608
	v_pk_fma_f32 v[238:239], v[58:59], v[94:95], v[212:213] op_sel:[0,1,0]
	v_mov_b32_dpp v231, v230 row_ror:8 row_mask:0xf bank_mask:0xf
	v_pk_fma_f32 v[206:207], v[88:89], v[230:231], v[232:233] op_sel_hi:[0,1,1] neg_lo:[1,0,0] neg_hi:[1,0,0]
	v_pk_fma_f32 v[208:209], v[88:89], v[230:231], v[234:235] op_sel:[1,0,0] neg_lo:[1,0,0] neg_hi:[1,0,0]
	v_pk_fma_f32 v[210:211], v[90:91], v[230:231], v[236:237] op_sel_hi:[0,1,1] neg_lo:[1,0,0] neg_hi:[1,0,0]
	v_pk_fma_f32 v[212:213], v[90:91], v[230:231], v[238:239] op_sel:[1,0,0] neg_lo:[1,0,0] neg_hi:[1,0,0]
	s_waitcnt lgkmcnt(6)
	ds_read_b128 v[56:59], v242 offset:46688
	v_pk_mul_f32 v[226:227], v[206:207], v[106:107] op_sel_hi:[1,0]
	v_pk_mul_f32 v[228:229], v[206:207], v[222:223] op_sel_hi:[1,0]
	v_pk_fma_f32 v[226:227], v[208:209], v[106:107], v[226:227] op_sel:[0,1,0]
	v_pk_fma_f32 v[228:229], v[208:209], v[222:223], v[228:229] op_sel:[0,1,0]
	v_pk_fma_f32 v[226:227], v[210:211], v[108:109], v[226:227] op_sel_hi:[1,0,1]
	v_pk_fma_f32 v[228:229], v[210:211], v[224:225], v[228:229] op_sel_hi:[1,0,1]
	v_pk_fma_f32 v[226:227], v[212:213], v[108:109], v[226:227] op_sel:[0,1,0]
	v_pk_fma_f32 v[228:229], v[212:213], v[224:225], v[228:229] op_sel:[0,1,0]
	ds_read_b128 v[84:87], v240 offset:11968
	v_add_f32_dpp v230, v227, v226 row_ror:8 row_mask:0xf bank_mask:0xf
	ds_read_b128 v[92:95], v240 offset:29376
	ds_read_b128 v[88:91], v240 offset:20672
	v_add_f32_dpp v230, v230, v230 quad_perm:[1,0,3,2] row_mask:0xf bank_mask:0xf
	ds_read_b128 v[222:225], v240 offset:37808
	v_pk_fma_f32 v[232:233], v[60:61], v[114:115], v[206:207] op_sel_hi:[1,0,1]
	v_add_f32_dpp v230, v230, v230 quad_perm:[2,3,0,1] row_mask:0xf bank_mask:0xf
	v_pk_fma_f32 v[234:235], v[60:61], v[114:115], v[208:209] op_sel:[0,1,0]
	v_pk_fma_f32 v[236:237], v[60:61], v[116:117], v[210:211] op_sel_hi:[1,0,1]
	v_add_f32_dpp v230, v230, v230 row_half_mirror row_mask:0xf bank_mask:0xf
	ds_write_b64 v217, v[228:229] offset:5184
	v_pk_fma_f32 v[238:239], v[60:61], v[116:117], v[212:213] op_sel:[0,1,0]
	v_mov_b32_dpp v231, v230 row_ror:8 row_mask:0xf bank_mask:0xf
	v_pk_fma_f32 v[206:207], v[110:111], v[230:231], v[232:233] op_sel_hi:[0,1,1] neg_lo:[1,0,0] neg_hi:[1,0,0]
	v_pk_fma_f32 v[208:209], v[110:111], v[230:231], v[234:235] op_sel:[1,0,0] neg_lo:[1,0,0] neg_hi:[1,0,0]
	v_pk_fma_f32 v[210:211], v[112:113], v[230:231], v[236:237] op_sel_hi:[0,1,1] neg_lo:[1,0,0] neg_hi:[1,0,0]
	v_pk_fma_f32 v[212:213], v[112:113], v[230:231], v[238:239] op_sel:[1,0,0] neg_lo:[1,0,0] neg_hi:[1,0,0]
	s_waitcnt lgkmcnt(7)
	v_pk_mul_f32 v[226:227], v[206:207], v[4:5] op_sel_hi:[1,0]
	v_pk_mul_f32 v[228:229], v[206:207], v[96:97] op_sel_hi:[1,0]
	v_pk_fma_f32 v[226:227], v[208:209], v[4:5], v[226:227] op_sel:[0,1,0]
	v_pk_fma_f32 v[228:229], v[208:209], v[96:97], v[228:229] op_sel:[0,1,0]
	v_pk_fma_f32 v[226:227], v[210:211], v[6:7], v[226:227] op_sel_hi:[1,0,1]
	v_pk_fma_f32 v[228:229], v[210:211], v[98:99], v[228:229] op_sel_hi:[1,0,1]
	v_pk_fma_f32 v[226:227], v[212:213], v[6:7], v[226:227] op_sel:[0,1,0]
	v_pk_fma_f32 v[228:229], v[212:213], v[98:99], v[228:229] op_sel:[0,1,0]
	ds_read_b128 v[106:109], v240 offset:12240
	v_add_f32_dpp v230, v227, v226 row_ror:8 row_mask:0xf bank_mask:0xf
	ds_read_b128 v[114:117], v240 offset:29648
	ds_read_b128 v[110:113], v240 offset:20944
	v_add_f32_dpp v230, v230, v230 quad_perm:[1,0,3,2] row_mask:0xf bank_mask:0xf
	ds_read_b128 v[96:99], v240 offset:38080
	v_pk_fma_f32 v[232:233], v[62:63], v[12:13], v[206:207] op_sel_hi:[1,0,1]
	v_add_f32_dpp v230, v230, v230 quad_perm:[2,3,0,1] row_mask:0xf bank_mask:0xf
	v_pk_fma_f32 v[234:235], v[62:63], v[12:13], v[208:209] op_sel:[0,1,0]
	v_pk_fma_f32 v[236:237], v[62:63], v[14:15], v[210:211] op_sel_hi:[1,0,1]
	v_add_f32_dpp v230, v230, v230 row_half_mirror row_mask:0xf bank_mask:0xf
	ds_write_b64 v217, v[228:229] offset:5760
	v_pk_fma_f32 v[238:239], v[62:63], v[14:15], v[212:213] op_sel:[0,1,0]
	v_mov_b32_dpp v231, v230 row_ror:8 row_mask:0xf bank_mask:0xf
	v_pk_fma_f32 v[206:207], v[8:9], v[230:231], v[232:233] op_sel_hi:[0,1,1] neg_lo:[1,0,0] neg_hi:[1,0,0]
	v_pk_fma_f32 v[208:209], v[8:9], v[230:231], v[234:235] op_sel:[1,0,0] neg_lo:[1,0,0] neg_hi:[1,0,0]
	v_pk_fma_f32 v[210:211], v[10:11], v[230:231], v[236:237] op_sel_hi:[0,1,1] neg_lo:[1,0,0] neg_hi:[1,0,0]
	v_pk_fma_f32 v[212:213], v[10:11], v[230:231], v[238:239] op_sel:[1,0,0] neg_lo:[1,0,0] neg_hi:[1,0,0]
	s_waitcnt lgkmcnt(6)
; template <int CTRL> __device__ __forceinline__ float dppf(float x) { return __builtin_bit_cast(float, __builtin_amdgcn_update_dpp(0, __builtin_bit_cast(int, x), CTRL, 0xF, 0xF, false)); }
; __device__ __forceinline__ void phase_rwkv_scan(const Fr& F, int jr) {
;     ...
;                         const f32x4 w4n = PW[pn * 16], k4n = PW[1024 + pn * 16], b4n = PW[2048 + pn * 16], d4n = PW[3072 + pn * 16], r4n = PR[pn * 16];
;                         const float vvn = PV[pn * 32];
;                         f32x2 t = S01 * k4.xy; t = S23 * k4.zw + t; float sa = t.x + t.y;
;                         sa += dppf<0x128>(sa);
;                         const f32x2 dv01 = d4.xy * vv, dv23 = d4.zw * vv;
;                         sa += dppf<0x124>(sa);
;                         const f32x2 e01 = S01 * w4.xy + dv01;
;                         sa += dppf<0x122>(sa);
;                         const f32x2 e23 = S23 * w4.zw + dv23;
;                         sa += dppf<0x121>(sa);
;                         S01 = e01 - b4.xy * sa; S23 = e23 - b4.zw * sa;
;                         f32x2 u = S01 * r4.xy; u = S23 * r4.zw + u;
;                         PY[pi * 64] = u.x + u.y;
;                         w4 = w4n; k4 = k4n; b4 = b4n; d4 = d4n; r4 = r4n; vv = vvn;
	ds_read_b128 v[60:63], v242 offset:47216
	v_pk_mul_f32 v[226:227], v[206:207], v[84:85] op_sel_hi:[1,0]
	v_pk_mul_f32 v[228:229], v[206:207], v[222:223] op_sel_hi:[1,0]
	v_pk_fma_f32 v[226:227], v[208:209], v[84:85], v[226:227] op_sel:[0,1,0]
	v_pk_fma_f32 v[228:229], v[208:209], v[222:223], v[228:229] op_sel:[0,1,0]
	v_pk_fma_f32 v[226:227], v[210:211], v[86:87], v[226:227] op_sel_hi:[1,0,1]
	v_pk_fma_f32 v[228:229], v[210:211], v[224:225], v[228:229] op_sel_hi:[1,0,1]
	v_pk_fma_f32 v[226:227], v[212:213], v[86:87], v[226:227] op_sel:[0,1,0]
	v_pk_fma_f32 v[228:229], v[212:213], v[224:225], v[228:229] op_sel:[0,1,0]
	ds_read_b128 v[4:7], v240 offset:12512
	v_add_f32_dpp v230, v227, v226 row_ror:8 row_mask:0xf bank_mask:0xf
	ds_read_b128 v[12:15], v240 offset:29920
	ds_read_b128 v[8:11], v240 offset:21216
	v_add_f32_dpp v230, v230, v230 quad_perm:[1,0,3,2] row_mask:0xf bank_mask:0xf
	ds_read_b128 v[222:225], v240 offset:38352
	v_pk_fma_f32 v[232:233], v[56:57], v[92:93], v[206:207] op_sel_hi:[1,0,1]
	v_add_f32_dpp v230, v230, v230 quad_perm:[2,3,0,1] row_mask:0xf bank_mask:0xf
	v_pk_fma_f32 v[234:235], v[56:57], v[92:93], v[208:209] op_sel:[0,1,0]
	v_pk_fma_f32 v[236:237], v[56:57], v[94:95], v[210:211] op_sel_hi:[1,0,1]
	v_add_f32_dpp v230, v230, v230 row_half_mirror row_mask:0xf bank_mask:0xf
	ds_write_b64 v217, v[228:229] offset:6336
	v_pk_fma_f32 v[238:239], v[56:57], v[94:95], v[212:213] op_sel:[0,1,0]
	v_mov_b32_dpp v231, v230 row_ror:8 row_mask:0xf bank_mask:0xf
	v_pk_fma_f32 v[206:207], v[88:89], v[230:231], v[232:233] op_sel_hi:[0,1,1] neg_lo:[1,0,0] neg_hi:[1,0,0]
	v_pk_fma_f32 v[208:209], v[88:89], v[230:231], v[234:235] op_sel:[1,0,0] neg_lo:[1,0,0] neg_hi:[1,0,0]
	v_pk_fma_f32 v[210:211], v[90:91], v[230:231], v[236:237] op_sel_hi:[0,1,1] neg_lo:[1,0,0] neg_hi:[1,0,0]
	v_pk_fma_f32 v[212:213], v[90:91], v[230:231], v[238:239] op_sel:[1,0,0] neg_lo:[1,0,0] neg_hi:[1,0,0]
	s_waitcnt lgkmcnt(7)
	v_pk_mul_f32 v[226:227], v[206:207], v[106:107] op_sel_hi:[1,0]
	v_pk_mul_f32 v[228:229], v[206:207], v[96:97] op_sel_hi:[1,0]
	v_pk_fma_f32 v[226:227], v[208:209], v[106:107], v[226:227] op_sel:[0,1,0]
	v_pk_fma_f32 v[228:229], v[208:209], v[96:97], v[228:229] op_sel:[0,1,0]
	v_pk_fma_f32 v[226:227], v[210:211], v[108:109], v[226:227] op_sel_hi:[1,0,1]
	v_pk_fma_f32 v[228:229], v[210:211], v[98:99], v[228:229] op_sel_hi:[1,0,1]
	v_pk_fma_f32 v[226:227], v[212:213], v[108:109], v[226:227] op_sel:[0,1,0]
	v_pk_fma_f32 v[228:229], v[212:213], v[98:99], v[228:229] op_sel:[0,1,0]
	ds_read_b128 v[84:87], v240 offset:12784
	v_add_f32_dpp v230, v227, v226 row_ror:8 row_mask:0xf bank_mask:0xf
	ds_read_b128 v[92:95], v240 offset:30192
	ds_read_b128 v[88:91], v240 offset:21488
	v_add_f32_dpp v230, v230, v230 quad_perm:[1,0,3,2] row_mask:0xf bank_mask:0xf
	ds_read_b128 v[96:99], v240 offset:38624
	ds_read_b128 v[80:83], v240 offset:4080
	v_add_f32_dpp v230, v230, v230 quad_perm:[2,3,0,1] row_mask:0xf bank_mask:0xf
	v_pk_fma_f32 v[232:233], v[58:59], v[114:115], v[206:207] op_sel_hi:[1,0,1]
	v_pk_fma_f32 v[234:235], v[58:59], v[114:115], v[208:209] op_sel:[0,1,0]
	v_add_f32_dpp v230, v230, v230 row_half_mirror row_mask:0xf bank_mask:0xf
	ds_write_b64 v217, v[228:229] offset:6912
	v_pk_fma_f32 v[236:237], v[58:59], v[116:117], v[210:211] op_sel_hi:[1,0,1]
	v_pk_fma_f32 v[238:239], v[58:59], v[116:117], v[212:213] op_sel:[0,1,0]
	v_mov_b32_dpp v231, v230 row_ror:8 row_mask:0xf bank_mask:0xf
	v_pk_fma_f32 v[206:207], v[110:111], v[230:231], v[232:233] op_sel_hi:[0,1,1] neg_lo:[1,0,0] neg_hi:[1,0,0]
	v_pk_fma_f32 v[208:209], v[110:111], v[230:231], v[234:235] op_sel:[1,0,0] neg_lo:[1,0,0] neg_hi:[1,0,0]
	v_pk_fma_f32 v[210:211], v[112:113], v[230:231], v[236:237] op_sel_hi:[0,1,1] neg_lo:[1,0,0] neg_hi:[1,0,0]
	v_pk_fma_f32 v[212:213], v[112:113], v[230:231], v[238:239] op_sel:[1,0,0] neg_lo:[1,0,0] neg_hi:[1,0,0]
	s_waitcnt lgkmcnt(7)
	ds_read_b128 v[56:59], v242 offset:47744
	v_pk_mul_f32 v[226:227], v[206:207], v[4:5] op_sel_hi:[1,0]
	v_pk_mul_f32 v[228:229], v[206:207], v[222:223] op_sel_hi:[1,0]
	v_pk_fma_f32 v[226:227], v[208:209], v[4:5], v[226:227] op_sel:[0,1,0]
	v_pk_fma_f32 v[228:229], v[208:209], v[222:223], v[228:229] op_sel:[0,1,0]
	v_pk_fma_f32 v[226:227], v[210:211], v[6:7], v[226:227] op_sel_hi:[1,0,1]
	v_pk_fma_f32 v[228:229], v[210:211], v[224:225], v[228:229] op_sel_hi:[1,0,1]
	v_pk_fma_f32 v[226:227], v[212:213], v[6:7], v[226:227] op_sel:[0,1,0]
	v_pk_fma_f32 v[228:229], v[212:213], v[224:225], v[228:229] op_sel:[0,1,0]
	ds_read_b128 v[106:109], v240 offset:13056
	v_add_f32_dpp v230, v227, v226 row_ror:8 row_mask:0xf bank_mask:0xf
	ds_read_b128 v[114:117], v240 offset:30464
	ds_read_b128 v[110:113], v240 offset:21760
	v_add_f32_dpp v230, v230, v230 quad_perm:[1,0,3,2] row_mask:0xf bank_mask:0xf
	ds_read_b128 v[222:225], v240 offset:38896
	v_pk_fma_f32 v[232:233], v[60:61], v[12:13], v[206:207] op_sel_hi:[1,0,1]
	v_add_f32_dpp v230, v230, v230 quad_perm:[2,3,0,1] row_mask:0xf bank_mask:0xf
	v_pk_fma_f32 v[234:235], v[60:61], v[12:13], v[208:209] op_sel:[0,1,0]
	v_pk_fma_f32 v[236:237], v[60:61], v[14:15], v[210:211] op_sel_hi:[1,0,1]
	v_add_f32_dpp v230, v230, v230 row_half_mirror row_mask:0xf bank_mask:0xf
	ds_write_b64 v217, v[228:229] offset:7488
	v_pk_fma_f32 v[238:239], v[60:61], v[14:15], v[212:213] op_sel:[0,1,0]
	v_mov_b32_dpp v231, v230 row_ror:8 row_mask:0xf bank_mask:0xf
	v_pk_fma_f32 v[206:207], v[8:9], v[230:231], v[232:233] op_sel_hi:[0,1,1] neg_lo:[1,0,0] neg_hi:[1,0,0]
	v_pk_fma_f32 v[208:209], v[8:9], v[230:231], v[234:235] op_sel:[1,0,0] neg_lo:[1,0,0] neg_hi:[1,0,0]
	v_pk_fma_f32 v[210:211], v[10:11], v[230:231], v[236:237] op_sel_hi:[0,1,1] neg_lo:[1,0,0] neg_hi:[1,0,0]
	v_pk_fma_f32 v[212:213], v[10:11], v[230:231], v[238:239] op_sel:[1,0,0] neg_lo:[1,0,0] neg_hi:[1,0,0]
	s_waitcnt lgkmcnt(8)
; __device__ __forceinline__ unsigned f2bf(float f) { unsigned u = __builtin_bit_cast(unsigned, f); return (u + 0x7fffu + ((u >> 16) & 1u)) >> 16; }
; template <int CTRL> __device__ __forceinline__ float dppf(float x) { return __builtin_bit_cast(float, __builtin_amdgcn_update_dpp(0, __builtin_bit_cast(int, x), CTRL, 0xF, 0xF, false)); }
; __device__ __forceinline__ void phase_rwkv_scan(const Fr& F, int jr) {
;     ...
;                         const f32x4 w4n = PW[pn * 16], k4n = PW[1024 + pn * 16], b4n = PW[2048 + pn * 16], d4n = PW[3072 + pn * 16], r4n = PR[pn * 16];
;                         const float vvn = PV[pn * 32];
;                         f32x2 t = S01 * k4.xy; t = S23 * k4.zw + t; float sa = t.x + t.y;
;                         sa += dppf<0x128>(sa);
;                         const f32x2 dv01 = d4.xy * vv, dv23 = d4.zw * vv;
;                         sa += dppf<0x124>(sa);
;                         const f32x2 e01 = S01 * w4.xy + dv01;
;                         sa += dppf<0x122>(sa);
;                         const f32x2 e23 = S23 * w4.zw + dv23;
;                         sa += dppf<0x121>(sa);
;                         S01 = e01 - b4.xy * sa; S23 = e23 - b4.zw * sa;
;                         f32x2 u = S01 * r4.xy; u = S23 * r4.zw + u;
;                         PY[pi * 64] = u.x + u.y;
;                         w4 = w4n; k4 = k4n; b4 = b4n; d4 = d4n; r4 = r4n; vv = vvn;
;                     }
;                     asm volatile("s_waitcnt lgkmcnt(0)" ::: "memory");
;                     {
;                         const int j = lane >> 2, q = lane & 3; const float* yp = Ypw + j * 64 + q * 16;
;                         const f32x4 a0 = *(const f32x4*)yp, a1 = *(const f32x4*)(yp + 4), a2 = *(const f32x4*)(yp + 8), a3 = *(const f32x4*)(yp + 12);
;                         const f32x4 ssum = (a0 + a1) + (a2 + a3); const float yv = (ssum.x + ssum.y) + (ssum.z + ssum.w);
;                         const size_t row = (size_t)b * TB + tokof(s, chunk * 64 + pg + j);
;                         Yb[row * D + h * 64 + 32 * half + 4 * wave + q] = (bf16)f2bf(yv);
;                     }
;                     asm volatile("s_waitcnt lgkmcnt(0)" ::: "memory");
	v_pk_mul_f32 v[226:227], v[206:207], v[84:85] op_sel_hi:[1,0]
	v_pk_mul_f32 v[228:229], v[206:207], v[96:97] op_sel_hi:[1,0]
	v_pk_fma_f32 v[226:227], v[208:209], v[84:85], v[226:227] op_sel:[0,1,0]
	v_pk_fma_f32 v[228:229], v[208:209], v[96:97], v[228:229] op_sel:[0,1,0]
	v_pk_fma_f32 v[226:227], v[210:211], v[86:87], v[226:227] op_sel_hi:[1,0,1]
	v_pk_fma_f32 v[228:229], v[210:211], v[98:99], v[228:229] op_sel_hi:[1,0,1]
	v_pk_fma_f32 v[226:227], v[212:213], v[86:87], v[226:227] op_sel:[0,1,0]
	v_pk_fma_f32 v[228:229], v[212:213], v[98:99], v[228:229] op_sel:[0,1,0]
	ds_read_b128 v[4:7], v240 offset:13328
	v_add_f32_dpp v230, v227, v226 row_ror:8 row_mask:0xf bank_mask:0xf
	ds_read_b128 v[12:15], v240 offset:30736
	ds_read_b128 v[8:11], v240 offset:22032
	v_add_f32_dpp v230, v230, v230 quad_perm:[1,0,3,2] row_mask:0xf bank_mask:0xf
	ds_read_b128 v[96:99], v240 offset:39168
	v_pk_fma_f32 v[232:233], v[62:63], v[92:93], v[206:207] op_sel_hi:[1,0,1]
	v_add_f32_dpp v230, v230, v230 quad_perm:[2,3,0,1] row_mask:0xf bank_mask:0xf
	v_pk_fma_f32 v[234:235], v[62:63], v[92:93], v[208:209] op_sel:[0,1,0]
	v_pk_fma_f32 v[236:237], v[62:63], v[94:95], v[210:211] op_sel_hi:[1,0,1]
	v_add_f32_dpp v230, v230, v230 row_half_mirror row_mask:0xf bank_mask:0xf
	ds_write_b64 v217, v[228:229] offset:8064
	v_pk_fma_f32 v[238:239], v[62:63], v[94:95], v[212:213] op_sel:[0,1,0]
	v_mov_b32_dpp v231, v230 row_ror:8 row_mask:0xf bank_mask:0xf
	v_pk_fma_f32 v[206:207], v[88:89], v[230:231], v[232:233] op_sel_hi:[0,1,1] neg_lo:[1,0,0] neg_hi:[1,0,0]
	v_pk_fma_f32 v[208:209], v[88:89], v[230:231], v[234:235] op_sel:[1,0,0] neg_lo:[1,0,0] neg_hi:[1,0,0]
	v_pk_fma_f32 v[210:211], v[90:91], v[230:231], v[236:237] op_sel_hi:[0,1,1] neg_lo:[1,0,0] neg_hi:[1,0,0]
	v_pk_fma_f32 v[212:213], v[90:91], v[230:231], v[238:239] op_sel:[1,0,0] neg_lo:[1,0,0] neg_hi:[1,0,0]
	s_waitcnt lgkmcnt(6)
	v_pk_mul_f32 v[228:229], v[206:207], v[222:223] op_sel_hi:[1,0]
	v_add_u32_e32 v243, s15, v219
	v_pk_fma_f32 v[228:229], v[208:209], v[222:223], v[228:229] op_sel:[0,1,0]
	v_lshl_add_u32 v243, v243, 11, v220
	v_pk_fma_f32 v[228:229], v[210:211], v[224:225], v[228:229] op_sel_hi:[1,0,1]
	v_pk_fma_f32 v[228:229], v[212:213], v[224:225], v[228:229] op_sel:[0,1,0]
	s_waitcnt lgkmcnt(5)
	ds_write_b64 v217, v[228:229] offset:8640
	v_pk_mul_f32 v[206:207], v[206:207], v[80:81] op_sel_hi:[1,0]
	v_pk_mul_f32 v[208:209], v[208:209], v[80:81] op_sel:[0,1]
	v_pk_mul_f32 v[210:211], v[210:211], v[82:83] op_sel_hi:[1,0]
	v_pk_mul_f32 v[212:213], v[212:213], v[82:83] op_sel:[0,1]
	ds_read_b128 v[24:27], v218 offset:0
	ds_read_b128 v[28:31], v218 offset:16
	ds_read_b128 v[32:35], v218 offset:32
	ds_read_b128 v[36:39], v218 offset:48
	ds_read_b128 v[40:43], v218 offset:64
	ds_read_b128 v[44:47], v218 offset:80
	ds_read_b128 v[48:51], v218 offset:96
	ds_read_b128 v[52:55], v218 offset:112
	s_waitcnt lgkmcnt(4)
	v_pk_add_f32 v[24:25], v[24:25], v[26:27]
	v_pk_add_f32 v[28:29], v[28:29], v[30:31]
	v_pk_add_f32 v[32:33], v[32:33], v[34:35]
	v_pk_add_f32 v[36:37], v[36:37], v[38:39]
	v_pk_add_f32 v[24:25], v[24:25], v[28:29]
	s_waitcnt lgkmcnt(0)
	v_pk_add_f32 v[40:41], v[40:41], v[42:43]
	v_pk_add_f32 v[44:45], v[44:45], v[46:47]
	v_pk_add_f32 v[32:33], v[32:33], v[36:37]
	v_pk_add_f32 v[48:49], v[48:49], v[50:51]
	v_pk_add_f32 v[52:53], v[52:53], v[54:55]
	v_pk_add_f32 v[40:41], v[40:41], v[44:45]
	v_pk_add_f32 v[24:25], v[24:25], v[32:33]
	v_pk_add_f32 v[48:49], v[48:49], v[52:53]
	s_add_i32 s15, s15, s19
	v_pk_add_f32 v[40:41], v[40:41], v[48:49]
	v_pk_add_f32 v[24:25], v[24:25], v[40:41] op_sel:[0,1] op_sel_hi:[1,0]
	v_cvt_pk_bf16_f32 v244, v24, v25
	global_store_dword v243, v244, s[20:21]
	v_pk_mul_f32 v[226:227], v[206:207], v[106:107] op_sel_hi:[1,0]
	v_pk_fma_f32 v[232:233], v[56:57], v[114:115], v[206:207] op_sel_hi:[1,0,1]
	v_pk_fma_f32 v[226:227], v[208:209], v[106:107], v[226:227] op_sel:[0,1,0]
	v_pk_fma_f32 v[234:235], v[56:57], v[114:115], v[208:209] op_sel:[0,1,0]
	v_pk_fma_f32 v[226:227], v[210:211], v[108:109], v[226:227] op_sel_hi:[1,0,1]
	v_pk_fma_f32 v[236:237], v[56:57], v[116:117], v[210:211] op_sel_hi:[1,0,1]
	v_pk_fma_f32 v[226:227], v[212:213], v[108:109], v[226:227] op_sel:[0,1,0]
	v_pk_fma_f32 v[238:239], v[56:57], v[116:117], v[212:213] op_sel:[0,1,0]
	ds_read_b128 v[92:95], v240 offset:31008
	v_add_f32_dpp v230, v227, v226 row_ror:8 row_mask:0xf bank_mask:0xf
	ds_read_b128 v[88:91], v240 offset:22304
	ds_read_b128 v[84:87], v240 offset:13600
	v_add_f32_dpp v230, v230, v230 quad_perm:[1,0,3,2] row_mask:0xf bank_mask:0xf
	ds_read_b128 v[222:225], v240 offset:39440
	ds_read_b128 v[60:63], v242 offset:48272
	v_add_f32_dpp v230, v230, v230 quad_perm:[2,3,0,1] row_mask:0xf bank_mask:0xf
	s_nop 1
	v_add_f32_dpp v230, v230, v230 row_half_mirror row_mask:0xf bank_mask:0xf
	s_nop 1
	v_mov_b32_dpp v231, v230 row_ror:8 row_mask:0xf bank_mask:0xf
	v_pk_fma_f32 v[206:207], v[110:111], v[230:231], v[232:233] op_sel_hi:[0,1,1] neg_lo:[1,0,0] neg_hi:[1,0,0]
	v_pk_fma_f32 v[208:209], v[110:111], v[230:231], v[234:235] op_sel:[1,0,0] neg_lo:[1,0,0] neg_hi:[1,0,0]
	v_pk_fma_f32 v[210:211], v[112:113], v[230:231], v[236:237] op_sel_hi:[0,1,1] neg_lo:[1,0,0] neg_hi:[1,0,0]
	v_pk_fma_f32 v[212:213], v[112:113], v[230:231], v[238:239] op_sel:[1,0,0] neg_lo:[1,0,0] neg_hi:[1,0,0]
	v_pk_mul_f32 v[226:227], v[206:207], v[4:5] op_sel_hi:[1,0]
	v_pk_mul_f32 v[228:229], v[206:207], v[96:97] op_sel_hi:[1,0]
	v_pk_fma_f32 v[226:227], v[208:209], v[4:5], v[226:227] op_sel:[0,1,0]
	v_pk_fma_f32 v[228:229], v[208:209], v[96:97], v[228:229] op_sel:[0,1,0]
	v_pk_fma_f32 v[226:227], v[210:211], v[6:7], v[226:227] op_sel_hi:[1,0,1]
; template <int CTRL> __device__ __forceinline__ float dppf(float x) { return __builtin_bit_cast(float, __builtin_amdgcn_update_dpp(0, __builtin_bit_cast(int, x), CTRL, 0xF, 0xF, false)); }
; __device__ __forceinline__ void phase_rwkv_scan(const Fr& F, int jr) {
;     ...
;                         const f32x4 w4n = PW[pn * 16], k4n = PW[1024 + pn * 16], b4n = PW[2048 + pn * 16], d4n = PW[3072 + pn * 16], r4n = PR[pn * 16];
;                         const float vvn = PV[pn * 32];
;                         f32x2 t = S01 * k4.xy; t = S23 * k4.zw + t; float sa = t.x + t.y;
;                         sa += dppf<0x128>(sa);
;                         const f32x2 dv01 = d4.xy * vv, dv23 = d4.zw * vv;
;                         sa += dppf<0x124>(sa);
;                         const f32x2 e01 = S01 * w4.xy + dv01;
;                         sa += dppf<0x122>(sa);
;                         const f32x2 e23 = S23 * w4.zw + dv23;
;                         sa += dppf<0x121>(sa);
;                         S01 = e01 - b4.xy * sa; S23 = e23 - b4.zw * sa;
;                         f32x2 u = S01 * r4.xy; u = S23 * r4.zw + u;
;                         PY[pi * 64] = u.x + u.y;
;                         w4 = w4n; k4 = k4n; b4 = b4n; d4 = d4n; r4 = r4n; vv = vvn;
	v_pk_fma_f32 v[228:229], v[210:211], v[98:99], v[228:229] op_sel_hi:[1,0,1]
	v_pk_fma_f32 v[226:227], v[212:213], v[6:7], v[226:227] op_sel:[0,1,0]
	v_pk_fma_f32 v[228:229], v[212:213], v[98:99], v[228:229] op_sel:[0,1,0]
	ds_read_b128 v[106:109], v240 offset:13872
	v_add_f32_dpp v230, v227, v226 row_ror:8 row_mask:0xf bank_mask:0xf
	ds_read_b128 v[114:117], v240 offset:31280
	ds_read_b128 v[110:113], v240 offset:22576
	v_add_f32_dpp v230, v230, v230 quad_perm:[1,0,3,2] row_mask:0xf bank_mask:0xf
	ds_read_b128 v[96:99], v240 offset:39712
	v_pk_fma_f32 v[232:233], v[58:59], v[12:13], v[206:207] op_sel_hi:[1,0,1]
	v_add_f32_dpp v230, v230, v230 quad_perm:[2,3,0,1] row_mask:0xf bank_mask:0xf
	v_pk_fma_f32 v[234:235], v[58:59], v[12:13], v[208:209] op_sel:[0,1,0]
	v_pk_fma_f32 v[236:237], v[58:59], v[14:15], v[210:211] op_sel_hi:[1,0,1]
	v_add_f32_dpp v230, v230, v230 row_half_mirror row_mask:0xf bank_mask:0xf
	ds_write_b64 v217, v[228:229] offset:0
	v_pk_fma_f32 v[238:239], v[58:59], v[14:15], v[212:213] op_sel:[0,1,0]
	v_mov_b32_dpp v231, v230 row_ror:8 row_mask:0xf bank_mask:0xf
	v_pk_fma_f32 v[206:207], v[8:9], v[230:231], v[232:233] op_sel_hi:[0,1,1] neg_lo:[1,0,0] neg_hi:[1,0,0]
	v_pk_fma_f32 v[208:209], v[8:9], v[230:231], v[234:235] op_sel:[1,0,0] neg_lo:[1,0,0] neg_hi:[1,0,0]
	v_pk_fma_f32 v[210:211], v[10:11], v[230:231], v[236:237] op_sel_hi:[0,1,1] neg_lo:[1,0,0] neg_hi:[1,0,0]
	v_pk_fma_f32 v[212:213], v[10:11], v[230:231], v[238:239] op_sel:[1,0,0] neg_lo:[1,0,0] neg_hi:[1,0,0]
	s_waitcnt lgkmcnt(5)
	ds_read_b128 v[56:59], v242 offset:48800
	v_pk_mul_f32 v[226:227], v[206:207], v[84:85] op_sel_hi:[1,0]
	v_pk_mul_f32 v[228:229], v[206:207], v[222:223] op_sel_hi:[1,0]
	v_pk_fma_f32 v[226:227], v[208:209], v[84:85], v[226:227] op_sel:[0,1,0]
	v_pk_fma_f32 v[228:229], v[208:209], v[222:223], v[228:229] op_sel:[0,1,0]
	v_pk_fma_f32 v[226:227], v[210:211], v[86:87], v[226:227] op_sel_hi:[1,0,1]
	v_pk_fma_f32 v[228:229], v[210:211], v[224:225], v[228:229] op_sel_hi:[1,0,1]
	v_pk_fma_f32 v[226:227], v[212:213], v[86:87], v[226:227] op_sel:[0,1,0]
	v_pk_fma_f32 v[228:229], v[212:213], v[224:225], v[228:229] op_sel:[0,1,0]
	ds_read_b128 v[4:7], v240 offset:14144
	v_add_f32_dpp v230, v227, v226 row_ror:8 row_mask:0xf bank_mask:0xf
	ds_read_b128 v[12:15], v240 offset:31552
	ds_read_b128 v[8:11], v240 offset:22848
	v_add_f32_dpp v230, v230, v230 quad_perm:[1,0,3,2] row_mask:0xf bank_mask:0xf
	ds_read_b128 v[222:225], v240 offset:39984
	v_pk_fma_f32 v[232:233], v[60:61], v[92:93], v[206:207] op_sel_hi:[1,0,1]
	v_add_f32_dpp v230, v230, v230 quad_perm:[2,3,0,1] row_mask:0xf bank_mask:0xf
	v_pk_fma_f32 v[234:235], v[60:61], v[92:93], v[208:209] op_sel:[0,1,0]
	v_pk_fma_f32 v[236:237], v[60:61], v[94:95], v[210:211] op_sel_hi:[1,0,1]
	v_add_f32_dpp v230, v230, v230 row_half_mirror row_mask:0xf bank_mask:0xf
	ds_write_b64 v217, v[228:229] offset:576
	v_pk_fma_f32 v[238:239], v[60:61], v[94:95], v[212:213] op_sel:[0,1,0]
	v_mov_b32_dpp v231, v230 row_ror:8 row_mask:0xf bank_mask:0xf
	v_pk_fma_f32 v[206:207], v[88:89], v[230:231], v[232:233] op_sel_hi:[0,1,1] neg_lo:[1,0,0] neg_hi:[1,0,0]
	v_pk_fma_f32 v[208:209], v[88:89], v[230:231], v[234:235] op_sel:[1,0,0] neg_lo:[1,0,0] neg_hi:[1,0,0]
	v_pk_fma_f32 v[210:211], v[90:91], v[230:231], v[236:237] op_sel_hi:[0,1,1] neg_lo:[1,0,0] neg_hi:[1,0,0]
	v_pk_fma_f32 v[212:213], v[90:91], v[230:231], v[238:239] op_sel:[1,0,0] neg_lo:[1,0,0] neg_hi:[1,0,0]
	s_waitcnt lgkmcnt(7)
	v_pk_mul_f32 v[226:227], v[206:207], v[106:107] op_sel_hi:[1,0]
	v_pk_mul_f32 v[228:229], v[206:207], v[96:97] op_sel_hi:[1,0]
	v_pk_fma_f32 v[226:227], v[208:209], v[106:107], v[226:227] op_sel:[0,1,0]
	v_pk_fma_f32 v[228:229], v[208:209], v[96:97], v[228:229] op_sel:[0,1,0]
	v_pk_fma_f32 v[226:227], v[210:211], v[108:109], v[226:227] op_sel_hi:[1,0,1]
	v_pk_fma_f32 v[228:229], v[210:211], v[98:99], v[228:229] op_sel_hi:[1,0,1]
	v_pk_fma_f32 v[226:227], v[212:213], v[108:109], v[226:227] op_sel:[0,1,0]
	v_pk_fma_f32 v[228:229], v[212:213], v[98:99], v[228:229] op_sel:[0,1,0]
	ds_read_b128 v[84:87], v240 offset:14416
	v_add_f32_dpp v230, v227, v226 row_ror:8 row_mask:0xf bank_mask:0xf
	ds_read_b128 v[92:95], v240 offset:31824
	ds_read_b128 v[88:91], v240 offset:23120
	v_add_f32_dpp v230, v230, v230 quad_perm:[1,0,3,2] row_mask:0xf bank_mask:0xf
	ds_read_b128 v[96:99], v240 offset:40256
	v_pk_fma_f32 v[232:233], v[62:63], v[114:115], v[206:207] op_sel_hi:[1,0,1]
	v_add_f32_dpp v230, v230, v230 quad_perm:[2,3,0,1] row_mask:0xf bank_mask:0xf
	v_pk_fma_f32 v[234:235], v[62:63], v[114:115], v[208:209] op_sel:[0,1,0]
	v_pk_fma_f32 v[236:237], v[62:63], v[116:117], v[210:211] op_sel_hi:[1,0,1]
	v_add_f32_dpp v230, v230, v230 row_half_mirror row_mask:0xf bank_mask:0xf
	ds_write_b64 v217, v[228:229] offset:1152
	v_pk_fma_f32 v[238:239], v[62:63], v[116:117], v[212:213] op_sel:[0,1,0]
	v_mov_b32_dpp v231, v230 row_ror:8 row_mask:0xf bank_mask:0xf
	v_pk_fma_f32 v[206:207], v[110:111], v[230:231], v[232:233] op_sel_hi:[0,1,1] neg_lo:[1,0,0] neg_hi:[1,0,0]
	v_pk_fma_f32 v[208:209], v[110:111], v[230:231], v[234:235] op_sel:[1,0,0] neg_lo:[1,0,0] neg_hi:[1,0,0]
	v_pk_fma_f32 v[210:211], v[112:113], v[230:231], v[236:237] op_sel_hi:[0,1,1] neg_lo:[1,0,0] neg_hi:[1,0,0]
	v_pk_fma_f32 v[212:213], v[112:113], v[230:231], v[238:239] op_sel:[1,0,0] neg_lo:[1,0,0] neg_hi:[1,0,0]
	s_waitcnt lgkmcnt(6)
; template <int CTRL> __device__ __forceinline__ float dppf(float x) { return __builtin_bit_cast(float, __builtin_amdgcn_update_dpp(0, __builtin_bit_cast(int, x), CTRL, 0xF, 0xF, false)); }
; __device__ __forceinline__ void phase_rwkv_scan(const Fr& F, int jr) {
;     ...
;                         const f32x4 w4n = PW[pn * 16], k4n = PW[1024 + pn * 16], b4n = PW[2048 + pn * 16], d4n = PW[3072 + pn * 16], r4n = PR[pn * 16];
;                         const float vvn = PV[pn * 32];
;                         f32x2 t = S01 * k4.xy; t = S23 * k4.zw + t; float sa = t.x + t.y;
;                         sa += dppf<0x128>(sa);
;                         const f32x2 dv01 = d4.xy * vv, dv23 = d4.zw * vv;
;                         sa += dppf<0x124>(sa);
;                         const f32x2 e01 = S01 * w4.xy + dv01;
;                         sa += dppf<0x122>(sa);
;                         const f32x2 e23 = S23 * w4.zw + dv23;
;                         sa += dppf<0x121>(sa);
;                         S01 = e01 - b4.xy * sa; S23 = e23 - b4.zw * sa;
;                         f32x2 u = S01 * r4.xy; u = S23 * r4.zw + u;
;                         PY[pi * 64] = u.x + u.y;
;                         w4 = w4n; k4 = k4n; b4 = b4n; d4 = d4n; r4 = r4n; vv = vvn;
	ds_read_b128 v[60:63], v242 offset:49328
	v_pk_mul_f32 v[226:227], v[206:207], v[4:5] op_sel_hi:[1,0]
	v_pk_mul_f32 v[228:229], v[206:207], v[222:223] op_sel_hi:[1,0]
	v_pk_fma_f32 v[226:227], v[208:209], v[4:5], v[226:227] op_sel:[0,1,0]
	v_pk_fma_f32 v[228:229], v[208:209], v[222:223], v[228:229] op_sel:[0,1,0]
	v_pk_fma_f32 v[226:227], v[210:211], v[6:7], v[226:227] op_sel_hi:[1,0,1]
	v_pk_fma_f32 v[228:229], v[210:211], v[224:225], v[228:229] op_sel_hi:[1,0,1]
	v_pk_fma_f32 v[226:227], v[212:213], v[6:7], v[226:227] op_sel:[0,1,0]
	v_pk_fma_f32 v[228:229], v[212:213], v[224:225], v[228:229] op_sel:[0,1,0]
	ds_read_b128 v[106:109], v240 offset:14688
	v_add_f32_dpp v230, v227, v226 row_ror:8 row_mask:0xf bank_mask:0xf
	ds_read_b128 v[114:117], v240 offset:32096
	ds_read_b128 v[110:113], v240 offset:23392
	v_add_f32_dpp v230, v230, v230 quad_perm:[1,0,3,2] row_mask:0xf bank_mask:0xf
	ds_read_b128 v[222:225], v240 offset:40528
	v_pk_fma_f32 v[232:233], v[56:57], v[12:13], v[206:207] op_sel_hi:[1,0,1]
	v_add_f32_dpp v230, v230, v230 quad_perm:[2,3,0,1] row_mask:0xf bank_mask:0xf
	v_pk_fma_f32 v[234:235], v[56:57], v[12:13], v[208:209] op_sel:[0,1,0]
	v_pk_fma_f32 v[236:237], v[56:57], v[14:15], v[210:211] op_sel_hi:[1,0,1]
	v_add_f32_dpp v230, v230, v230 row_half_mirror row_mask:0xf bank_mask:0xf
	ds_write_b64 v217, v[228:229] offset:1728
	v_pk_fma_f32 v[238:239], v[56:57], v[14:15], v[212:213] op_sel:[0,1,0]
	v_mov_b32_dpp v231, v230 row_ror:8 row_mask:0xf bank_mask:0xf
	v_pk_fma_f32 v[206:207], v[8:9], v[230:231], v[232:233] op_sel_hi:[0,1,1] neg_lo:[1,0,0] neg_hi:[1,0,0]
	v_pk_fma_f32 v[208:209], v[8:9], v[230:231], v[234:235] op_sel:[1,0,0] neg_lo:[1,0,0] neg_hi:[1,0,0]
	v_pk_fma_f32 v[210:211], v[10:11], v[230:231], v[236:237] op_sel_hi:[0,1,1] neg_lo:[1,0,0] neg_hi:[1,0,0]
	v_pk_fma_f32 v[212:213], v[10:11], v[230:231], v[238:239] op_sel:[1,0,0] neg_lo:[1,0,0] neg_hi:[1,0,0]
	s_waitcnt lgkmcnt(7)
	v_pk_mul_f32 v[226:227], v[206:207], v[84:85] op_sel_hi:[1,0]
	v_pk_mul_f32 v[228:229], v[206:207], v[96:97] op_sel_hi:[1,0]
	v_pk_fma_f32 v[226:227], v[208:209], v[84:85], v[226:227] op_sel:[0,1,0]
	v_pk_fma_f32 v[228:229], v[208:209], v[96:97], v[228:229] op_sel:[0,1,0]
	v_pk_fma_f32 v[226:227], v[210:211], v[86:87], v[226:227] op_sel_hi:[1,0,1]
	v_pk_fma_f32 v[228:229], v[210:211], v[98:99], v[228:229] op_sel_hi:[1,0,1]
	v_pk_fma_f32 v[226:227], v[212:213], v[86:87], v[226:227] op_sel:[0,1,0]
	v_pk_fma_f32 v[228:229], v[212:213], v[98:99], v[228:229] op_sel:[0,1,0]
	ds_read_b128 v[4:7], v240 offset:14960
	v_add_f32_dpp v230, v227, v226 row_ror:8 row_mask:0xf bank_mask:0xf
	ds_read_b128 v[12:15], v240 offset:32368
	ds_read_b128 v[8:11], v240 offset:23664
	v_add_f32_dpp v230, v230, v230 quad_perm:[1,0,3,2] row_mask:0xf bank_mask:0xf
	ds_read_b128 v[96:99], v240 offset:40800
	v_pk_fma_f32 v[232:233], v[58:59], v[92:93], v[206:207] op_sel_hi:[1,0,1]
	v_add_f32_dpp v230, v230, v230 quad_perm:[2,3,0,1] row_mask:0xf bank_mask:0xf
	v_pk_fma_f32 v[234:235], v[58:59], v[92:93], v[208:209] op_sel:[0,1,0]
	v_pk_fma_f32 v[236:237], v[58:59], v[94:95], v[210:211] op_sel_hi:[1,0,1]
	v_add_f32_dpp v230, v230, v230 row_half_mirror row_mask:0xf bank_mask:0xf
	ds_write_b64 v217, v[228:229] offset:2304
	v_pk_fma_f32 v[238:239], v[58:59], v[94:95], v[212:213] op_sel:[0,1,0]
	v_mov_b32_dpp v231, v230 row_ror:8 row_mask:0xf bank_mask:0xf
	v_pk_fma_f32 v[206:207], v[88:89], v[230:231], v[232:233] op_sel_hi:[0,1,1] neg_lo:[1,0,0] neg_hi:[1,0,0]
	v_pk_fma_f32 v[208:209], v[88:89], v[230:231], v[234:235] op_sel:[1,0,0] neg_lo:[1,0,0] neg_hi:[1,0,0]
	v_pk_fma_f32 v[210:211], v[90:91], v[230:231], v[236:237] op_sel_hi:[0,1,1] neg_lo:[1,0,0] neg_hi:[1,0,0]
	v_pk_fma_f32 v[212:213], v[90:91], v[230:231], v[238:239] op_sel:[1,0,0] neg_lo:[1,0,0] neg_hi:[1,0,0]
	s_waitcnt lgkmcnt(6)
	ds_read_b128 v[56:59], v242 offset:49856
	v_pk_mul_f32 v[226:227], v[206:207], v[106:107] op_sel_hi:[1,0]
	v_pk_mul_f32 v[228:229], v[206:207], v[222:223] op_sel_hi:[1,0]
	v_pk_fma_f32 v[226:227], v[208:209], v[106:107], v[226:227] op_sel:[0,1,0]
	v_pk_fma_f32 v[228:229], v[208:209], v[222:223], v[228:229] op_sel:[0,1,0]
	v_pk_fma_f32 v[226:227], v[210:211], v[108:109], v[226:227] op_sel_hi:[1,0,1]
	v_pk_fma_f32 v[228:229], v[210:211], v[224:225], v[228:229] op_sel_hi:[1,0,1]
	v_pk_fma_f32 v[226:227], v[212:213], v[108:109], v[226:227] op_sel:[0,1,0]
	v_pk_fma_f32 v[228:229], v[212:213], v[224:225], v[228:229] op_sel:[0,1,0]
	ds_read_b128 v[84:87], v240 offset:15232
	v_add_f32_dpp v230, v227, v226 row_ror:8 row_mask:0xf bank_mask:0xf
	ds_read_b128 v[92:95], v240 offset:32640
	ds_read_b128 v[88:91], v240 offset:23936
	v_add_f32_dpp v230, v230, v230 quad_perm:[1,0,3,2] row_mask:0xf bank_mask:0xf
	ds_read_b128 v[222:225], v240 offset:41072
	v_pk_fma_f32 v[232:233], v[60:61], v[114:115], v[206:207] op_sel_hi:[1,0,1]
	v_add_f32_dpp v230, v230, v230 quad_perm:[2,3,0,1] row_mask:0xf bank_mask:0xf
	v_pk_fma_f32 v[234:235], v[60:61], v[114:115], v[208:209] op_sel:[0,1,0]
	v_pk_fma_f32 v[236:237], v[60:61], v[116:117], v[210:211] op_sel_hi:[1,0,1]
	v_add_f32_dpp v230, v230, v230 row_half_mirror row_mask:0xf bank_mask:0xf
	ds_write_b64 v217, v[228:229] offset:2880
	v_pk_fma_f32 v[238:239], v[60:61], v[116:117], v[212:213] op_sel:[0,1,0]
	v_mov_b32_dpp v231, v230 row_ror:8 row_mask:0xf bank_mask:0xf
	v_pk_fma_f32 v[206:207], v[110:111], v[230:231], v[232:233] op_sel_hi:[0,1,1] neg_lo:[1,0,0] neg_hi:[1,0,0]
	v_pk_fma_f32 v[208:209], v[110:111], v[230:231], v[234:235] op_sel:[1,0,0] neg_lo:[1,0,0] neg_hi:[1,0,0]
	v_pk_fma_f32 v[210:211], v[112:113], v[230:231], v[236:237] op_sel_hi:[0,1,1] neg_lo:[1,0,0] neg_hi:[1,0,0]
	v_pk_fma_f32 v[212:213], v[112:113], v[230:231], v[238:239] op_sel:[1,0,0] neg_lo:[1,0,0] neg_hi:[1,0,0]
	s_waitcnt lgkmcnt(7)
; template <int CTRL> __device__ __forceinline__ float dppf(float x) { return __builtin_bit_cast(float, __builtin_amdgcn_update_dpp(0, __builtin_bit_cast(int, x), CTRL, 0xF, 0xF, false)); }
; __device__ __forceinline__ void phase_rwkv_scan(const Fr& F, int jr) {
;     ...
;                         const f32x4 w4n = PW[pn * 16], k4n = PW[1024 + pn * 16], b4n = PW[2048 + pn * 16], d4n = PW[3072 + pn * 16], r4n = PR[pn * 16];
;                         const float vvn = PV[pn * 32];
;                         f32x2 t = S01 * k4.xy; t = S23 * k4.zw + t; float sa = t.x + t.y;
;                         sa += dppf<0x128>(sa);
;                         const f32x2 dv01 = d4.xy * vv, dv23 = d4.zw * vv;
;                         sa += dppf<0x124>(sa);
;                         const f32x2 e01 = S01 * w4.xy + dv01;
;                         sa += dppf<0x122>(sa);
;                         const f32x2 e23 = S23 * w4.zw + dv23;
;                         sa += dppf<0x121>(sa);
;                         S01 = e01 - b4.xy * sa; S23 = e23 - b4.zw * sa;
;                         f32x2 u = S01 * r4.xy; u = S23 * r4.zw + u;
;                         PY[pi * 64] = u.x + u.y;
;                         w4 = w4n; k4 = k4n; b4 = b4n; d4 = d4n; r4 = r4n; vv = vvn;
	v_pk_mul_f32 v[226:227], v[206:207], v[4:5] op_sel_hi:[1,0]
	v_pk_mul_f32 v[228:229], v[206:207], v[96:97] op_sel_hi:[1,0]
	v_pk_fma_f32 v[226:227], v[208:209], v[4:5], v[226:227] op_sel:[0,1,0]
	v_pk_fma_f32 v[228:229], v[208:209], v[96:97], v[228:229] op_sel:[0,1,0]
	v_pk_fma_f32 v[226:227], v[210:211], v[6:7], v[226:227] op_sel_hi:[1,0,1]
	v_pk_fma_f32 v[228:229], v[210:211], v[98:99], v[228:229] op_sel_hi:[1,0,1]
	v_pk_fma_f32 v[226:227], v[212:213], v[6:7], v[226:227] op_sel:[0,1,0]
	v_pk_fma_f32 v[228:229], v[212:213], v[98:99], v[228:229] op_sel:[0,1,0]
	ds_read_b128 v[106:109], v240 offset:15504
	v_add_f32_dpp v230, v227, v226 row_ror:8 row_mask:0xf bank_mask:0xf
	ds_read_b128 v[114:117], v240 offset:32912
	ds_read_b128 v[110:113], v240 offset:24208
	v_add_f32_dpp v230, v230, v230 quad_perm:[1,0,3,2] row_mask:0xf bank_mask:0xf
	ds_read_b128 v[96:99], v240 offset:41344
	v_pk_fma_f32 v[232:233], v[62:63], v[12:13], v[206:207] op_sel_hi:[1,0,1]
	v_add_f32_dpp v230, v230, v230 quad_perm:[2,3,0,1] row_mask:0xf bank_mask:0xf
	v_pk_fma_f32 v[234:235], v[62:63], v[12:13], v[208:209] op_sel:[0,1,0]
	v_pk_fma_f32 v[236:237], v[62:63], v[14:15], v[210:211] op_sel_hi:[1,0,1]
	v_add_f32_dpp v230, v230, v230 row_half_mirror row_mask:0xf bank_mask:0xf
	ds_write_b64 v217, v[228:229] offset:3456
	v_pk_fma_f32 v[238:239], v[62:63], v[14:15], v[212:213] op_sel:[0,1,0]
	v_mov_b32_dpp v231, v230 row_ror:8 row_mask:0xf bank_mask:0xf
	v_pk_fma_f32 v[206:207], v[8:9], v[230:231], v[232:233] op_sel_hi:[0,1,1] neg_lo:[1,0,0] neg_hi:[1,0,0]
	v_pk_fma_f32 v[208:209], v[8:9], v[230:231], v[234:235] op_sel:[1,0,0] neg_lo:[1,0,0] neg_hi:[1,0,0]
	v_pk_fma_f32 v[210:211], v[10:11], v[230:231], v[236:237] op_sel_hi:[0,1,1] neg_lo:[1,0,0] neg_hi:[1,0,0]
	v_pk_fma_f32 v[212:213], v[10:11], v[230:231], v[238:239] op_sel:[1,0,0] neg_lo:[1,0,0] neg_hi:[1,0,0]
	s_waitcnt lgkmcnt(6)
	ds_read_b128 v[60:63], v242 offset:50384
	v_pk_mul_f32 v[226:227], v[206:207], v[84:85] op_sel_hi:[1,0]
	v_pk_mul_f32 v[228:229], v[206:207], v[222:223] op_sel_hi:[1,0]
	v_pk_fma_f32 v[226:227], v[208:209], v[84:85], v[226:227] op_sel:[0,1,0]
	v_pk_fma_f32 v[228:229], v[208:209], v[222:223], v[228:229] op_sel:[0,1,0]
	v_pk_fma_f32 v[226:227], v[210:211], v[86:87], v[226:227] op_sel_hi:[1,0,1]
	v_pk_fma_f32 v[228:229], v[210:211], v[224:225], v[228:229] op_sel_hi:[1,0,1]
	v_pk_fma_f32 v[226:227], v[212:213], v[86:87], v[226:227] op_sel:[0,1,0]
	v_pk_fma_f32 v[228:229], v[212:213], v[224:225], v[228:229] op_sel:[0,1,0]
	ds_read_b128 v[4:7], v240 offset:15776
	v_add_f32_dpp v230, v227, v226 row_ror:8 row_mask:0xf bank_mask:0xf
	ds_read_b128 v[12:15], v240 offset:33184
	ds_read_b128 v[8:11], v240 offset:24480
	v_add_f32_dpp v230, v230, v230 quad_perm:[1,0,3,2] row_mask:0xf bank_mask:0xf
	ds_read_b128 v[222:225], v240 offset:41616
	v_pk_fma_f32 v[232:233], v[56:57], v[92:93], v[206:207] op_sel_hi:[1,0,1]
	v_add_f32_dpp v230, v230, v230 quad_perm:[2,3,0,1] row_mask:0xf bank_mask:0xf
	v_pk_fma_f32 v[234:235], v[56:57], v[92:93], v[208:209] op_sel:[0,1,0]
	v_pk_fma_f32 v[236:237], v[56:57], v[94:95], v[210:211] op_sel_hi:[1,0,1]
	v_add_f32_dpp v230, v230, v230 row_half_mirror row_mask:0xf bank_mask:0xf
	ds_write_b64 v217, v[228:229] offset:4032
	v_pk_fma_f32 v[238:239], v[56:57], v[94:95], v[212:213] op_sel:[0,1,0]
	v_mov_b32_dpp v231, v230 row_ror:8 row_mask:0xf bank_mask:0xf
	v_pk_fma_f32 v[206:207], v[88:89], v[230:231], v[232:233] op_sel_hi:[0,1,1] neg_lo:[1,0,0] neg_hi:[1,0,0]
	v_pk_fma_f32 v[208:209], v[88:89], v[230:231], v[234:235] op_sel:[1,0,0] neg_lo:[1,0,0] neg_hi:[1,0,0]
	v_pk_fma_f32 v[210:211], v[90:91], v[230:231], v[236:237] op_sel_hi:[0,1,1] neg_lo:[1,0,0] neg_hi:[1,0,0]
	v_pk_fma_f32 v[212:213], v[90:91], v[230:231], v[238:239] op_sel:[1,0,0] neg_lo:[1,0,0] neg_hi:[1,0,0]
	s_waitcnt lgkmcnt(7)
	v_pk_mul_f32 v[226:227], v[206:207], v[106:107] op_sel_hi:[1,0]
	v_pk_mul_f32 v[228:229], v[206:207], v[96:97] op_sel_hi:[1,0]
	v_pk_fma_f32 v[226:227], v[208:209], v[106:107], v[226:227] op_sel:[0,1,0]
	v_pk_fma_f32 v[228:229], v[208:209], v[96:97], v[228:229] op_sel:[0,1,0]
	v_pk_fma_f32 v[226:227], v[210:211], v[108:109], v[226:227] op_sel_hi:[1,0,1]
	v_pk_fma_f32 v[228:229], v[210:211], v[98:99], v[228:229] op_sel_hi:[1,0,1]
	v_pk_fma_f32 v[226:227], v[212:213], v[108:109], v[226:227] op_sel:[0,1,0]
	v_pk_fma_f32 v[228:229], v[212:213], v[98:99], v[228:229] op_sel:[0,1,0]
	ds_read_b128 v[84:87], v240 offset:16048
	v_add_f32_dpp v230, v227, v226 row_ror:8 row_mask:0xf bank_mask:0xf
	ds_read_b128 v[92:95], v240 offset:33456
	ds_read_b128 v[88:91], v240 offset:24752
	v_add_f32_dpp v230, v230, v230 quad_perm:[1,0,3,2] row_mask:0xf bank_mask:0xf
	ds_read_b128 v[96:99], v240 offset:41888
	v_pk_fma_f32 v[232:233], v[58:59], v[114:115], v[206:207] op_sel_hi:[1,0,1]
	v_add_f32_dpp v230, v230, v230 quad_perm:[2,3,0,1] row_mask:0xf bank_mask:0xf
	v_pk_fma_f32 v[234:235], v[58:59], v[114:115], v[208:209] op_sel:[0,1,0]
	v_pk_fma_f32 v[236:237], v[58:59], v[116:117], v[210:211] op_sel_hi:[1,0,1]
	v_add_f32_dpp v230, v230, v230 row_half_mirror row_mask:0xf bank_mask:0xf
	ds_write_b64 v217, v[228:229] offset:4608
	v_pk_fma_f32 v[238:239], v[58:59], v[116:117], v[212:213] op_sel:[0,1,0]
	v_mov_b32_dpp v231, v230 row_ror:8 row_mask:0xf bank_mask:0xf
	v_pk_fma_f32 v[206:207], v[110:111], v[230:231], v[232:233] op_sel_hi:[0,1,1] neg_lo:[1,0,0] neg_hi:[1,0,0]
	v_pk_fma_f32 v[208:209], v[110:111], v[230:231], v[234:235] op_sel:[1,0,0] neg_lo:[1,0,0] neg_hi:[1,0,0]
	v_pk_fma_f32 v[210:211], v[112:113], v[230:231], v[236:237] op_sel_hi:[0,1,1] neg_lo:[1,0,0] neg_hi:[1,0,0]
	v_pk_fma_f32 v[212:213], v[112:113], v[230:231], v[238:239] op_sel:[1,0,0] neg_lo:[1,0,0] neg_hi:[1,0,0]
	s_waitcnt lgkmcnt(6)
; template <int CTRL> __device__ __forceinline__ float dppf(float x) { return __builtin_bit_cast(float, __builtin_amdgcn_update_dpp(0, __builtin_bit_cast(int, x), CTRL, 0xF, 0xF, false)); }
; __device__ __forceinline__ void phase_rwkv_scan(const Fr& F, int jr) {
;     ...
;                         const f32x4 w4n = PW[pn * 16], k4n = PW[1024 + pn * 16], b4n = PW[2048 + pn * 16], d4n = PW[3072 + pn * 16], r4n = PR[pn * 16];
;                         const float vvn = PV[pn * 32];
;                         f32x2 t = S01 * k4.xy; t = S23 * k4.zw + t; float sa = t.x + t.y;
;                         sa += dppf<0x128>(sa);
;                         const f32x2 dv01 = d4.xy * vv, dv23 = d4.zw * vv;
;                         sa += dppf<0x124>(sa);
;                         const f32x2 e01 = S01 * w4.xy + dv01;
;                         sa += dppf<0x122>(sa);
;                         const f32x2 e23 = S23 * w4.zw + dv23;
;                         sa += dppf<0x121>(sa);
;                         S01 = e01 - b4.xy * sa; S23 = e23 - b4.zw * sa;
;                         f32x2 u = S01 * r4.xy; u = S23 * r4.zw + u;
;                         PY[pi * 64] = u.x + u.y;
;                         w4 = w4n; k4 = k4n; b4 = b4n; d4 = d4n; r4 = r4n; vv = vvn;
	ds_read_b128 v[56:59], v242 offset:50912
	v_pk_mul_f32 v[226:227], v[206:207], v[4:5] op_sel_hi:[1,0]
	v_pk_mul_f32 v[228:229], v[206:207], v[222:223] op_sel_hi:[1,0]
	v_pk_fma_f32 v[226:227], v[208:209], v[4:5], v[226:227] op_sel:[0,1,0]
	v_pk_fma_f32 v[228:229], v[208:209], v[222:223], v[228:229] op_sel:[0,1,0]
	v_pk_fma_f32 v[226:227], v[210:211], v[6:7], v[226:227] op_sel_hi:[1,0,1]
	v_pk_fma_f32 v[228:229], v[210:211], v[224:225], v[228:229] op_sel_hi:[1,0,1]
	v_pk_fma_f32 v[226:227], v[212:213], v[6:7], v[226:227] op_sel:[0,1,0]
	v_pk_fma_f32 v[228:229], v[212:213], v[224:225], v[228:229] op_sel:[0,1,0]
	ds_read_b128 v[106:109], v240 offset:16320
	v_add_f32_dpp v230, v227, v226 row_ror:8 row_mask:0xf bank_mask:0xf
	ds_read_b128 v[114:117], v240 offset:33728
	ds_read_b128 v[110:113], v240 offset:25024
	v_add_f32_dpp v230, v230, v230 quad_perm:[1,0,3,2] row_mask:0xf bank_mask:0xf
	ds_read_b128 v[222:225], v240 offset:42160
	v_pk_fma_f32 v[232:233], v[60:61], v[12:13], v[206:207] op_sel_hi:[1,0,1]
	v_add_f32_dpp v230, v230, v230 quad_perm:[2,3,0,1] row_mask:0xf bank_mask:0xf
	v_pk_fma_f32 v[234:235], v[60:61], v[12:13], v[208:209] op_sel:[0,1,0]
	v_pk_fma_f32 v[236:237], v[60:61], v[14:15], v[210:211] op_sel_hi:[1,0,1]
	v_add_f32_dpp v230, v230, v230 row_half_mirror row_mask:0xf bank_mask:0xf
	ds_write_b64 v217, v[228:229] offset:5184
	v_pk_fma_f32 v[238:239], v[60:61], v[14:15], v[212:213] op_sel:[0,1,0]
	v_mov_b32_dpp v231, v230 row_ror:8 row_mask:0xf bank_mask:0xf
	v_pk_fma_f32 v[206:207], v[8:9], v[230:231], v[232:233] op_sel_hi:[0,1,1] neg_lo:[1,0,0] neg_hi:[1,0,0]
	v_pk_fma_f32 v[208:209], v[8:9], v[230:231], v[234:235] op_sel:[1,0,0] neg_lo:[1,0,0] neg_hi:[1,0,0]
	v_pk_fma_f32 v[210:211], v[10:11], v[230:231], v[236:237] op_sel_hi:[0,1,1] neg_lo:[1,0,0] neg_hi:[1,0,0]
	v_pk_fma_f32 v[212:213], v[10:11], v[230:231], v[238:239] op_sel:[1,0,0] neg_lo:[1,0,0] neg_hi:[1,0,0]
	s_waitcnt lgkmcnt(7)
	v_pk_mul_f32 v[226:227], v[206:207], v[84:85] op_sel_hi:[1,0]
	v_pk_mul_f32 v[228:229], v[206:207], v[96:97] op_sel_hi:[1,0]
	v_pk_fma_f32 v[226:227], v[208:209], v[84:85], v[226:227] op_sel:[0,1,0]
	v_pk_fma_f32 v[228:229], v[208:209], v[96:97], v[228:229] op_sel:[0,1,0]
	v_pk_fma_f32 v[226:227], v[210:211], v[86:87], v[226:227] op_sel_hi:[1,0,1]
	v_pk_fma_f32 v[228:229], v[210:211], v[98:99], v[228:229] op_sel_hi:[1,0,1]
	v_pk_fma_f32 v[226:227], v[212:213], v[86:87], v[226:227] op_sel:[0,1,0]
	v_pk_fma_f32 v[228:229], v[212:213], v[98:99], v[228:229] op_sel:[0,1,0]
	ds_read_b128 v[4:7], v240 offset:16592
	v_add_f32_dpp v230, v227, v226 row_ror:8 row_mask:0xf bank_mask:0xf
	ds_read_b128 v[12:15], v240 offset:34000
	ds_read_b128 v[8:11], v240 offset:25296
	v_add_f32_dpp v230, v230, v230 quad_perm:[1,0,3,2] row_mask:0xf bank_mask:0xf
	ds_read_b128 v[96:99], v240 offset:42432
	v_pk_fma_f32 v[232:233], v[62:63], v[92:93], v[206:207] op_sel_hi:[1,0,1]
	v_add_f32_dpp v230, v230, v230 quad_perm:[2,3,0,1] row_mask:0xf bank_mask:0xf
	v_pk_fma_f32 v[234:235], v[62:63], v[92:93], v[208:209] op_sel:[0,1,0]
	v_pk_fma_f32 v[236:237], v[62:63], v[94:95], v[210:211] op_sel_hi:[1,0,1]
	v_add_f32_dpp v230, v230, v230 row_half_mirror row_mask:0xf bank_mask:0xf
	ds_write_b64 v217, v[228:229] offset:5760
	v_pk_fma_f32 v[238:239], v[62:63], v[94:95], v[212:213] op_sel:[0,1,0]
	v_mov_b32_dpp v231, v230 row_ror:8 row_mask:0xf bank_mask:0xf
	v_pk_fma_f32 v[206:207], v[88:89], v[230:231], v[232:233] op_sel_hi:[0,1,1] neg_lo:[1,0,0] neg_hi:[1,0,0]
	v_pk_fma_f32 v[208:209], v[88:89], v[230:231], v[234:235] op_sel:[1,0,0] neg_lo:[1,0,0] neg_hi:[1,0,0]
	v_pk_fma_f32 v[210:211], v[90:91], v[230:231], v[236:237] op_sel_hi:[0,1,1] neg_lo:[1,0,0] neg_hi:[1,0,0]
	v_pk_fma_f32 v[212:213], v[90:91], v[230:231], v[238:239] op_sel:[1,0,0] neg_lo:[1,0,0] neg_hi:[1,0,0]
	s_waitcnt lgkmcnt(6)
	ds_read_b128 v[60:63], v242 offset:51440
	v_pk_mul_f32 v[226:227], v[206:207], v[106:107] op_sel_hi:[1,0]
	v_pk_mul_f32 v[228:229], v[206:207], v[222:223] op_sel_hi:[1,0]
	v_pk_fma_f32 v[226:227], v[208:209], v[106:107], v[226:227] op_sel:[0,1,0]
	v_pk_fma_f32 v[228:229], v[208:209], v[222:223], v[228:229] op_sel:[0,1,0]
	v_pk_fma_f32 v[226:227], v[210:211], v[108:109], v[226:227] op_sel_hi:[1,0,1]
	v_pk_fma_f32 v[228:229], v[210:211], v[224:225], v[228:229] op_sel_hi:[1,0,1]
	v_pk_fma_f32 v[226:227], v[212:213], v[108:109], v[226:227] op_sel:[0,1,0]
	v_pk_fma_f32 v[228:229], v[212:213], v[224:225], v[228:229] op_sel:[0,1,0]
	ds_read_b128 v[84:87], v240 offset:16864
	v_add_f32_dpp v230, v227, v226 row_ror:8 row_mask:0xf bank_mask:0xf
	ds_read_b128 v[92:95], v240 offset:34272
	ds_read_b128 v[88:91], v240 offset:25568
	v_add_f32_dpp v230, v230, v230 quad_perm:[1,0,3,2] row_mask:0xf bank_mask:0xf
	ds_read_b128 v[222:225], v240 offset:42704
	v_pk_fma_f32 v[232:233], v[56:57], v[114:115], v[206:207] op_sel_hi:[1,0,1]
	v_add_f32_dpp v230, v230, v230 quad_perm:[2,3,0,1] row_mask:0xf bank_mask:0xf
	v_pk_fma_f32 v[234:235], v[56:57], v[114:115], v[208:209] op_sel:[0,1,0]
	v_pk_fma_f32 v[236:237], v[56:57], v[116:117], v[210:211] op_sel_hi:[1,0,1]
	v_add_f32_dpp v230, v230, v230 row_half_mirror row_mask:0xf bank_mask:0xf
	ds_write_b64 v217, v[228:229] offset:6336
	v_pk_fma_f32 v[238:239], v[56:57], v[116:117], v[212:213] op_sel:[0,1,0]
	v_mov_b32_dpp v231, v230 row_ror:8 row_mask:0xf bank_mask:0xf
	v_pk_fma_f32 v[206:207], v[110:111], v[230:231], v[232:233] op_sel_hi:[0,1,1] neg_lo:[1,0,0] neg_hi:[1,0,0]
	v_pk_fma_f32 v[208:209], v[110:111], v[230:231], v[234:235] op_sel:[1,0,0] neg_lo:[1,0,0] neg_hi:[1,0,0]
	v_pk_fma_f32 v[210:211], v[112:113], v[230:231], v[236:237] op_sel_hi:[0,1,1] neg_lo:[1,0,0] neg_hi:[1,0,0]
	v_pk_fma_f32 v[212:213], v[112:113], v[230:231], v[238:239] op_sel:[1,0,0] neg_lo:[1,0,0] neg_hi:[1,0,0]
	s_waitcnt lgkmcnt(7)
; template <int CTRL> __device__ __forceinline__ float dppf(float x) { return __builtin_bit_cast(float, __builtin_amdgcn_update_dpp(0, __builtin_bit_cast(int, x), CTRL, 0xF, 0xF, false)); }
; __device__ __forceinline__ void phase_rwkv_scan(const Fr& F, int jr) {
;     ...
;                         const f32x4 w4n = PW[pn * 16], k4n = PW[1024 + pn * 16], b4n = PW[2048 + pn * 16], d4n = PW[3072 + pn * 16], r4n = PR[pn * 16];
;                         const float vvn = PV[pn * 32];
;                         f32x2 t = S01 * k4.xy; t = S23 * k4.zw + t; float sa = t.x + t.y;
;                         sa += dppf<0x128>(sa);
;                         const f32x2 dv01 = d4.xy * vv, dv23 = d4.zw * vv;
;                         sa += dppf<0x124>(sa);
;                         const f32x2 e01 = S01 * w4.xy + dv01;
;                         sa += dppf<0x122>(sa);
;                         const f32x2 e23 = S23 * w4.zw + dv23;
;                         sa += dppf<0x121>(sa);
;                         S01 = e01 - b4.xy * sa; S23 = e23 - b4.zw * sa;
;                         f32x2 u = S01 * r4.xy; u = S23 * r4.zw + u;
;                         PY[pi * 64] = u.x + u.y;
;                         w4 = w4n; k4 = k4n; b4 = b4n; d4 = d4n; r4 = r4n; vv = vvn;
	v_pk_mul_f32 v[226:227], v[206:207], v[4:5] op_sel_hi:[1,0]
	v_pk_mul_f32 v[228:229], v[206:207], v[96:97] op_sel_hi:[1,0]
	v_pk_fma_f32 v[226:227], v[208:209], v[4:5], v[226:227] op_sel:[0,1,0]
	v_pk_fma_f32 v[228:229], v[208:209], v[96:97], v[228:229] op_sel:[0,1,0]
	v_pk_fma_f32 v[226:227], v[210:211], v[6:7], v[226:227] op_sel_hi:[1,0,1]
	v_pk_fma_f32 v[228:229], v[210:211], v[98:99], v[228:229] op_sel_hi:[1,0,1]
	v_pk_fma_f32 v[226:227], v[212:213], v[6:7], v[226:227] op_sel:[0,1,0]
	v_pk_fma_f32 v[228:229], v[212:213], v[98:99], v[228:229] op_sel:[0,1,0]
	ds_read_b128 v[106:109], v240 offset:17136
	v_add_f32_dpp v230, v227, v226 row_ror:8 row_mask:0xf bank_mask:0xf
	ds_read_b128 v[114:117], v240 offset:34544
	ds_read_b128 v[110:113], v240 offset:25840
	v_add_f32_dpp v230, v230, v230 quad_perm:[1,0,3,2] row_mask:0xf bank_mask:0xf
	ds_read_b128 v[96:99], v240 offset:42976
	ds_read_b128 v[102:105], v240 offset:8432
	v_add_f32_dpp v230, v230, v230 quad_perm:[2,3,0,1] row_mask:0xf bank_mask:0xf
	v_pk_fma_f32 v[232:233], v[58:59], v[12:13], v[206:207] op_sel_hi:[1,0,1]
	v_pk_fma_f32 v[234:235], v[58:59], v[12:13], v[208:209] op_sel:[0,1,0]
	v_add_f32_dpp v230, v230, v230 row_half_mirror row_mask:0xf bank_mask:0xf
	ds_write_b64 v217, v[228:229] offset:6912
	v_pk_fma_f32 v[236:237], v[58:59], v[14:15], v[210:211] op_sel_hi:[1,0,1]
	v_pk_fma_f32 v[238:239], v[58:59], v[14:15], v[212:213] op_sel:[0,1,0]
	v_mov_b32_dpp v231, v230 row_ror:8 row_mask:0xf bank_mask:0xf
	v_pk_fma_f32 v[206:207], v[8:9], v[230:231], v[232:233] op_sel_hi:[0,1,1] neg_lo:[1,0,0] neg_hi:[1,0,0]
	v_pk_fma_f32 v[208:209], v[8:9], v[230:231], v[234:235] op_sel:[1,0,0] neg_lo:[1,0,0] neg_hi:[1,0,0]
	v_pk_fma_f32 v[210:211], v[10:11], v[230:231], v[236:237] op_sel_hi:[0,1,1] neg_lo:[1,0,0] neg_hi:[1,0,0]
	v_pk_fma_f32 v[212:213], v[10:11], v[230:231], v[238:239] op_sel:[1,0,0] neg_lo:[1,0,0] neg_hi:[1,0,0]
	s_waitcnt lgkmcnt(7)
	v_pk_mul_f32 v[226:227], v[206:207], v[84:85] op_sel_hi:[1,0]
	v_pk_mul_f32 v[228:229], v[206:207], v[222:223] op_sel_hi:[1,0]
	v_pk_fma_f32 v[226:227], v[208:209], v[84:85], v[226:227] op_sel:[0,1,0]
	v_pk_fma_f32 v[228:229], v[208:209], v[222:223], v[228:229] op_sel:[0,1,0]
	v_pk_fma_f32 v[226:227], v[210:211], v[86:87], v[226:227] op_sel_hi:[1,0,1]
	v_pk_fma_f32 v[228:229], v[210:211], v[224:225], v[228:229] op_sel_hi:[1,0,1]
	v_pk_fma_f32 v[226:227], v[212:213], v[86:87], v[226:227] op_sel:[0,1,0]
	v_pk_fma_f32 v[228:229], v[212:213], v[224:225], v[228:229] op_sel:[0,1,0]
	s_nop 0
	v_add_f32_dpp v230, v227, v226 row_ror:8 row_mask:0xf bank_mask:0xf
	s_nop 1
	v_add_f32_dpp v230, v230, v230 quad_perm:[1,0,3,2] row_mask:0xf bank_mask:0xf
	ds_read_b128 v[222:225], v240 offset:43248
	v_pk_fma_f32 v[232:233], v[60:61], v[92:93], v[206:207] op_sel_hi:[1,0,1]
	v_add_f32_dpp v230, v230, v230 quad_perm:[2,3,0,1] row_mask:0xf bank_mask:0xf
	v_pk_fma_f32 v[234:235], v[60:61], v[92:93], v[208:209] op_sel:[0,1,0]
	v_pk_fma_f32 v[236:237], v[60:61], v[94:95], v[210:211] op_sel_hi:[1,0,1]
	v_add_f32_dpp v230, v230, v230 row_half_mirror row_mask:0xf bank_mask:0xf
	ds_write_b64 v217, v[228:229] offset:7488
	v_pk_fma_f32 v[238:239], v[60:61], v[94:95], v[212:213] op_sel:[0,1,0]
	v_mov_b32_dpp v231, v230 row_ror:8 row_mask:0xf bank_mask:0xf
	v_pk_fma_f32 v[206:207], v[88:89], v[230:231], v[232:233] op_sel_hi:[0,1,1] neg_lo:[1,0,0] neg_hi:[1,0,0]
	v_pk_fma_f32 v[208:209], v[88:89], v[230:231], v[234:235] op_sel:[1,0,0] neg_lo:[1,0,0] neg_hi:[1,0,0]
	v_pk_fma_f32 v[210:211], v[90:91], v[230:231], v[236:237] op_sel_hi:[0,1,1] neg_lo:[1,0,0] neg_hi:[1,0,0]
	v_pk_fma_f32 v[212:213], v[90:91], v[230:231], v[238:239] op_sel:[1,0,0] neg_lo:[1,0,0] neg_hi:[1,0,0]
	s_waitcnt lgkmcnt(4)
; __device__ __forceinline__ unsigned f2bf(float f) { unsigned u = __builtin_bit_cast(unsigned, f); return (u + 0x7fffu + ((u >> 16) & 1u)) >> 16; }
; template <int CTRL> __device__ __forceinline__ float dppf(float x) { return __builtin_bit_cast(float, __builtin_amdgcn_update_dpp(0, __builtin_bit_cast(int, x), CTRL, 0xF, 0xF, false)); }
; __device__ __forceinline__ void phase_rwkv_scan(const Fr& F, int jr) {
;     ...
;                         const f32x4 w4n = PW[pn * 16], k4n = PW[1024 + pn * 16], b4n = PW[2048 + pn * 16], d4n = PW[3072 + pn * 16], r4n = PR[pn * 16];
;                         const float vvn = PV[pn * 32];
;                         f32x2 t = S01 * k4.xy; t = S23 * k4.zw + t; float sa = t.x + t.y;
;                         sa += dppf<0x128>(sa);
;                         const f32x2 dv01 = d4.xy * vv, dv23 = d4.zw * vv;
;                         sa += dppf<0x124>(sa);
;                         const f32x2 e01 = S01 * w4.xy + dv01;
;                         sa += dppf<0x122>(sa);
;                         const f32x2 e23 = S23 * w4.zw + dv23;
;                         sa += dppf<0x121>(sa);
;                         S01 = e01 - b4.xy * sa; S23 = e23 - b4.zw * sa;
;                         f32x2 u = S01 * r4.xy; u = S23 * r4.zw + u;
;                         PY[pi * 64] = u.x + u.y;
;                         w4 = w4n; k4 = k4n; b4 = b4n; d4 = d4n; r4 = r4n; vv = vvn;
;                     }
;                     asm volatile("s_waitcnt lgkmcnt(0)" ::: "memory");
;                     {
;                         const int j = lane >> 2, q = lane & 3; const float* yp = Ypw + j * 64 + q * 16;
;                         const f32x4 a0 = *(const f32x4*)yp, a1 = *(const f32x4*)(yp + 4), a2 = *(const f32x4*)(yp + 8), a3 = *(const f32x4*)(yp + 12);
;                         const f32x4 ssum = (a0 + a1) + (a2 + a3); const float yv = (ssum.x + ssum.y) + (ssum.z + ssum.w);
;                         const size_t row = (size_t)b * TB + tokof(s, chunk * 64 + pg + j);
;                         Yb[row * D + h * 64 + 32 * half + 4 * wave + q] = (bf16)f2bf(yv);
;                     }
;                     asm volatile("s_waitcnt lgkmcnt(0)" ::: "memory");
	v_pk_mul_f32 v[226:227], v[206:207], v[106:107] op_sel_hi:[1,0]
	v_pk_mul_f32 v[228:229], v[206:207], v[96:97] op_sel_hi:[1,0]
	v_pk_fma_f32 v[226:227], v[208:209], v[106:107], v[226:227] op_sel:[0,1,0]
	v_pk_fma_f32 v[228:229], v[208:209], v[96:97], v[228:229] op_sel:[0,1,0]
	v_pk_fma_f32 v[226:227], v[210:211], v[108:109], v[226:227] op_sel_hi:[1,0,1]
	v_pk_fma_f32 v[228:229], v[210:211], v[98:99], v[228:229] op_sel_hi:[1,0,1]
	v_pk_fma_f32 v[226:227], v[212:213], v[108:109], v[226:227] op_sel:[0,1,0]
	v_pk_fma_f32 v[228:229], v[212:213], v[98:99], v[228:229] op_sel:[0,1,0]
	s_nop 0
	v_add_f32_dpp v230, v227, v226 row_ror:8 row_mask:0xf bank_mask:0xf
	s_nop 1
	v_add_f32_dpp v230, v230, v230 quad_perm:[1,0,3,2] row_mask:0xf bank_mask:0xf
	v_pk_fma_f32 v[232:233], v[62:63], v[114:115], v[206:207] op_sel_hi:[1,0,1]
	v_pk_fma_f32 v[234:235], v[62:63], v[114:115], v[208:209] op_sel:[0,1,0]
	v_add_f32_dpp v230, v230, v230 quad_perm:[2,3,0,1] row_mask:0xf bank_mask:0xf
	v_pk_fma_f32 v[236:237], v[62:63], v[116:117], v[210:211] op_sel_hi:[1,0,1]
	v_pk_fma_f32 v[238:239], v[62:63], v[116:117], v[212:213] op_sel:[0,1,0]
	v_add_f32_dpp v230, v230, v230 row_half_mirror row_mask:0xf bank_mask:0xf
	ds_write_b64 v217, v[228:229] offset:8064
	s_nop 0
	v_mov_b32_dpp v231, v230 row_ror:8 row_mask:0xf bank_mask:0xf
	v_pk_fma_f32 v[206:207], v[110:111], v[230:231], v[232:233] op_sel_hi:[0,1,1] neg_lo:[1,0,0] neg_hi:[1,0,0]
	v_pk_fma_f32 v[208:209], v[110:111], v[230:231], v[234:235] op_sel:[1,0,0] neg_lo:[1,0,0] neg_hi:[1,0,0]
	v_pk_fma_f32 v[210:211], v[112:113], v[230:231], v[236:237] op_sel_hi:[0,1,1] neg_lo:[1,0,0] neg_hi:[1,0,0]
	v_pk_fma_f32 v[212:213], v[112:113], v[230:231], v[238:239] op_sel:[1,0,0] neg_lo:[1,0,0] neg_hi:[1,0,0]
	s_waitcnt lgkmcnt(2)
	v_pk_mul_f32 v[228:229], v[206:207], v[222:223] op_sel_hi:[1,0]
	v_add_u32_e32 v243, s15, v219
	v_pk_fma_f32 v[228:229], v[208:209], v[222:223], v[228:229] op_sel:[0,1,0]
	v_lshl_add_u32 v243, v243, 11, v220
	v_pk_fma_f32 v[228:229], v[210:211], v[224:225], v[228:229] op_sel_hi:[1,0,1]
	v_pk_fma_f32 v[228:229], v[212:213], v[224:225], v[228:229] op_sel:[0,1,0]
	s_waitcnt lgkmcnt(1)
	ds_write_b64 v217, v[228:229] offset:8640
	v_pk_mul_f32 v[206:207], v[206:207], v[102:103] op_sel_hi:[1,0]
	v_pk_mul_f32 v[208:209], v[208:209], v[102:103] op_sel:[0,1]
	v_pk_mul_f32 v[210:211], v[210:211], v[104:105] op_sel_hi:[1,0]
	v_pk_mul_f32 v[212:213], v[212:213], v[104:105] op_sel:[0,1]
	ds_read_b128 v[24:27], v218 offset:0
	ds_read_b128 v[28:31], v218 offset:16
	ds_read_b128 v[32:35], v218 offset:32
	ds_read_b128 v[36:39], v218 offset:48
	ds_read_b128 v[40:43], v218 offset:64
	ds_read_b128 v[44:47], v218 offset:80
	ds_read_b128 v[48:51], v218 offset:96
	ds_read_b128 v[52:55], v218 offset:112
	s_waitcnt lgkmcnt(4)
	v_pk_add_f32 v[24:25], v[24:25], v[26:27]
	v_pk_add_f32 v[28:29], v[28:29], v[30:31]
	v_pk_add_f32 v[32:33], v[32:33], v[34:35]
	v_pk_add_f32 v[36:37], v[36:37], v[38:39]
	v_pk_add_f32 v[24:25], v[24:25], v[28:29]
	s_waitcnt lgkmcnt(0)
	v_pk_add_f32 v[40:41], v[40:41], v[42:43]
	v_pk_add_f32 v[44:45], v[44:45], v[46:47]
	v_pk_add_f32 v[32:33], v[32:33], v[36:37]
	v_pk_add_f32 v[48:49], v[48:49], v[50:51]
	v_pk_add_f32 v[52:53], v[52:53], v[54:55]
	v_pk_add_f32 v[40:41], v[40:41], v[44:45]
	v_pk_add_f32 v[24:25], v[24:25], v[32:33]
	v_pk_add_f32 v[48:49], v[48:49], v[52:53]
	s_add_i32 s15, s15, s19
	v_pk_add_f32 v[40:41], v[40:41], v[48:49]
	v_pk_add_f32 v[24:25], v[24:25], v[40:41] op_sel:[0,1] op_sel_hi:[1,0]
	v_cvt_pk_bf16_f32 v244, v24, v25
	global_store_dword v243, v244, s[20:21]
	s_waitcnt lgkmcnt(0)
	s_add_i32 s10, s10, 1
	s_xor_b32 s11, s11, 0xcc00
	s_cmp_eq_u32 s10, 8
	s_cselect_b32 s17, s18, 0
	s_add_i32 s15, s15, s17
	s_barrier
	s_cmp_lt_u32 s10, 136
	s_cbranch_scc1 .Lrw0_shc
	s_setprio 0
	s_branch .Lrw0_end
